# also write-through late weight-copy stores and scan state stores, nt pooling slab loads (keep once-used streams out of L2); on top of v79
# baseline (speedup 1.0000x reference)
.LBB0_449:
	s_waitcnt lgkmcnt(3)
	v_perm_b32 v16, v7, v6, s40
	s_waitcnt lgkmcnt(2)
	v_perm_b32 v17, v9, v8, s40
	s_waitcnt lgkmcnt(1)
	v_perm_b32 v18, v11, v10, s40
	v_perm_b32 v6, v7, v6, s37
	v_perm_b32 v7, v9, v8, s37
	v_perm_b32 v8, v11, v10, s37
	v_ashrrev_i32_e32 v10, 31, v2
	s_waitcnt lgkmcnt(0)
	v_perm_b32 v19, v13, v12, s40
	v_perm_b32 v9, v13, v12, s37
	v_mul_lo_u32 v12, s21, v2
	v_mul_lo_u32 v13, s20, v10
	v_mad_u64_u32 v[10:11], s[18:19], s20, v2, 0
	v_add3_u32 v11, v11, v13, v12
	s_add_i32 s28, s28, -1
	v_lshl_add_u64 v[4:5], v[10:11], 1, v[4:5]
	s_cmp_eq_u32 s28, 0
	global_store_dwordx4 v[4:5], v[6:9], off sc1
	v_lshl_add_u64 v[4:5], s[20:21], 1, v[4:5]
	s_cselect_b64 s[18:19], -1, 0
	global_store_dwordx4 v[4:5], v[16:19], off sc1
	s_barrier

.LBB0_481:
	s_ashr_i32 s43, s42, 31
	s_lshl_b64 s[24:25], s[42:43], 1
	s_add_u32 s22, s22, s24
	s_addc_u32 s23, s23, s25
	v_lshlrev_b32_e32 v2, 1, v2
	v_lshl_add_u64 v[4:5], s[22:23], 0, v[2:3]
	v_ashrrev_i32_e32 v2, 31, v17
	s_waitcnt lgkmcnt(3)
	v_perm_b32 v18, v7, v6, s37
	s_waitcnt lgkmcnt(2)
	v_perm_b32 v19, v9, v8, s37
	s_waitcnt lgkmcnt(1)
	v_perm_b32 v20, v11, v10, s37
	s_waitcnt lgkmcnt(0)
	v_perm_b32 v21, v13, v12, s37
	v_perm_b32 v6, v7, v6, s40
	v_perm_b32 v7, v9, v8, s40
	v_perm_b32 v8, v11, v10, s40
	v_perm_b32 v9, v13, v12, s40
	v_mul_lo_u32 v12, s21, v17
	v_mul_lo_u32 v2, s20, v2
	v_mad_u64_u32 v[10:11], s[22:23], s20, v17, 0
	v_add3_u32 v11, v11, v2, v12
	v_lshl_add_u64 v[10:11], v[10:11], 1, v[4:5]
	global_store_dwordx4 v[10:11], v[18:21], off sc1
	v_lshl_add_u64 v[10:11], s[20:21], 1, v[10:11]
	v_ashrrev_i32_e32 v2, 3, v15
	global_store_dwordx4 v[10:11], v[6:9], off sc1
	s_andn2_b64 vcc, exec, s[38:39]
	s_mov_b64 s[22:23], -1
	v_lshlrev_b32_e32 v6, 2, v2
	v_add3_u32 v12, 0, v6, v16
	ds_read2_b32 v[6:7], v12 offset1:129
	v_add_u32_e32 v8, 0x400, v12
	v_add_u32_e32 v10, 0x800, v12
	v_add_u32_e32 v12, 0xc00, v12
	ds_read2_b32 v[8:9], v8 offset0:2 offset1:131
	ds_read2_b32 v[10:11], v10 offset0:4 offset1:133
	ds_read2_b32 v[12:13], v12 offset0:6 offset1:135
	v_lshlrev_b32_e32 v16, 1, v2
	v_add_u32_e32 v15, s26, v16
	s_cbranch_vccnz .LBB0_485
	v_cmp_lt_i32_e32 vcc, s34, v15
	s_and_b64 s[22:23], s[18:19], vcc
	v_mov_b32_e32 v2, v15
	s_and_saveexec_b64 s[18:19], s[22:23]
	v_add_u32_e32 v2, 0xfffffc00, v15
	v_lshlrev_b32_e32 v17, 1, v15
	v_lshrrev_b32_e32 v2, 3, v2
	v_and_b32_e32 v16, 0x7e, v16
	v_and_b32_e32 v2, 0x1fffff80, v2
	v_and_or_b32 v16, v17, s35, v16
	v_add3_u32 v2, v16, v2, s30
	s_or_b64 exec, exec, s[18:19]
	s_mov_b64 s[22:23], 0

.LBB0_592:
	s_lshl_b32 s20, s29, 7
	s_and_b64 s[18:19], s[18:19], exec
	s_cselect_b32 s19, 0, -1
	s_cselect_b32 s18, s27, 0xfffffc00
	s_add_u32 s21, s4, s30
	s_addc_u32 s29, s5, 0
	s_lshl_b32 s20, s20, 1
	s_add_u32 s20, s21, s20
	s_addc_u32 s21, s29, 0
	v_lshlrev_b32_e32 v4, 1, v2
	v_lshl_add_u64 v[136:137], s[20:21], 0, v[4:5]
	v_lshl_add_u64 v[136:137], v[136:137], 0, s[16:17]
	s_mov_b64 s[16:17], 0xa400200
	v_lshl_add_u64 v[138:139], v[136:137], 0, s[16:17]
	s_mov_b32 s16, 0xa400000
	v_add_co_u32_e32 v136, vcc, s16, v136
	s_waitcnt lgkmcnt(0)
	v_cvt_pk_bf16_f32 v3, v140, v141
	v_addc_co_u32_e32 v137, vcc, 0, v137, vcc
	global_store_short v[136:137], v3, off offset:512 sc1
	global_store_short_d16_hi v[138:139], v3, off offset:128 sc1
	v_lshl_add_u64 v[136:137], v[138:139], 0, s[18:19]
	v_pk_mul_f32 v[138:139], v[8:9], v[140:141] op_sel:[1,0]
	s_add_i32 s28, s28, s36
	v_pk_fma_f32 v[142:143], v[8:9], v[140:141], v[138:139] op_sel:[0,0,1] op_sel_hi:[1,1,0] neg_lo:[0,0,1] neg_hi:[0,0,1]
	v_pk_fma_f32 v[138:139], v[8:9], v[140:141], v[138:139] op_sel:[0,0,1] op_sel_hi:[0,1,0]
	v_mov_b32_e32 v143, v139
	v_pk_add_f32 v[134:135], v[142:143], v[134:135]
	s_cmpk_gt_i32 s28, 0x7f
	v_pk_mul_f32 v[138:139], v[8:9], v[134:135] op_sel:[1,0]
	v_cvt_pk_bf16_f32 v3, v134, v135
	v_pk_fma_f32 v[140:141], v[8:9], v[134:135], v[138:139] op_sel:[0,0,1] op_sel_hi:[1,1,0] neg_lo:[0,0,1] neg_hi:[0,0,1]
	v_pk_fma_f32 v[134:135], v[8:9], v[134:135], v[138:139] op_sel:[0,0,1] op_sel_hi:[0,1,0]
	v_mov_b32_e32 v141, v135
	v_pk_add_f32 v[132:133], v[140:141], v[132:133]
	global_store_short v[136:137], v3, off sc1
	global_store_short_d16_hi v[136:137], v3, off offset:128 sc1
	v_lshl_add_u64 v[136:137], v[136:137], 0, s[18:19]
	v_cvt_pk_bf16_f32 v3, v132, v133
	global_store_short v[136:137], v3, off sc1
	global_store_short_d16_hi v[136:137], v3, off offset:128 sc1
	v_lshl_add_u64 v[134:135], v[136:137], 0, s[18:19]
	v_pk_mul_f32 v[136:137], v[8:9], v[132:133] op_sel:[1,0]
	s_nop 0
	v_pk_fma_f32 v[138:139], v[8:9], v[132:133], v[136:137] op_sel:[0,0,1] op_sel_hi:[1,1,0] neg_lo:[0,0,1] neg_hi:[0,0,1]
	v_pk_fma_f32 v[132:133], v[8:9], v[132:133], v[136:137] op_sel:[0,0,1] op_sel_hi:[0,1,0]
	v_mov_b32_e32 v139, v133
	v_pk_add_f32 v[130:131], v[138:139], v[130:131]
	v_lshl_add_u64 v[132:133], v[134:135], 0, s[18:19]
	v_cvt_pk_bf16_f32 v3, v130, v131
	global_store_short v[134:135], v3, off sc1
	global_store_short_d16_hi v[134:135], v3, off offset:128 sc1
	v_pk_mul_f32 v[134:135], v[8:9], v[130:131] op_sel:[1,0]
	s_nop 0
	v_pk_fma_f32 v[136:137], v[8:9], v[130:131], v[134:135] op_sel:[0,0,1] op_sel_hi:[1,1,0] neg_lo:[0,0,1] neg_hi:[0,0,1]
	v_pk_fma_f32 v[130:131], v[8:9], v[130:131], v[134:135] op_sel:[0,0,1] op_sel_hi:[0,1,0]
	v_mov_b32_e32 v137, v131
	v_pk_add_f32 v[128:129], v[136:137], v[128:129]
	v_lshl_add_u64 v[130:131], v[132:133], 0, s[18:19]
	v_cvt_pk_bf16_f32 v3, v128, v129
	global_store_short v[132:133], v3, off sc1
	global_store_short_d16_hi v[132:133], v3, off offset:128 sc1
	v_pk_mul_f32 v[132:133], v[8:9], v[128:129] op_sel:[1,0]
	s_nop 0
	v_pk_fma_f32 v[134:135], v[8:9], v[128:129], v[132:133] op_sel:[0,0,1] op_sel_hi:[1,1,0] neg_lo:[0,0,1] neg_hi:[0,0,1]
	v_pk_fma_f32 v[128:129], v[8:9], v[128:129], v[132:133] op_sel:[0,0,1] op_sel_hi:[0,1,0]
	v_mov_b32_e32 v135, v129
	v_pk_add_f32 v[126:127], v[134:135], v[126:127]
	v_lshl_add_u64 v[128:129], v[130:131], 0, s[18:19]
	v_cvt_pk_bf16_f32 v3, v126, v127
	global_store_short v[130:131], v3, off sc1
	global_store_short_d16_hi v[130:131], v3, off offset:128 sc1
	v_pk_mul_f32 v[130:131], v[8:9], v[126:127] op_sel:[1,0]
	s_nop 0
	v_pk_fma_f32 v[132:133], v[8:9], v[126:127], v[130:131] op_sel:[0,0,1] op_sel_hi:[1,1,0] neg_lo:[0,0,1] neg_hi:[0,0,1]
	v_pk_fma_f32 v[126:127], v[8:9], v[126:127], v[130:131] op_sel:[0,0,1] op_sel_hi:[0,1,0]
	v_mov_b32_e32 v133, v127
	v_pk_add_f32 v[124:125], v[132:133], v[124:125]
	v_lshl_add_u64 v[126:127], v[128:129], 0, s[18:19]
	v_cvt_pk_bf16_f32 v3, v124, v125
	global_store_short v[128:129], v3, off sc1
	global_store_short_d16_hi v[128:129], v3, off offset:128 sc1
	v_pk_mul_f32 v[128:129], v[8:9], v[124:125] op_sel:[1,0]
	s_nop 0
	v_pk_fma_f32 v[130:131], v[8:9], v[124:125], v[128:129] op_sel:[0,0,1] op_sel_hi:[1,1,0] neg_lo:[0,0,1] neg_hi:[0,0,1]
	v_pk_fma_f32 v[124:125], v[8:9], v[124:125], v[128:129] op_sel:[0,0,1] op_sel_hi:[0,1,0]
	v_mov_b32_e32 v131, v125
	v_pk_add_f32 v[122:123], v[130:131], v[122:123]
	v_lshl_add_u64 v[124:125], v[126:127], 0, s[18:19]
	v_cvt_pk_bf16_f32 v3, v122, v123
	global_store_short v[126:127], v3, off sc1
	global_store_short_d16_hi v[126:127], v3, off offset:128 sc1
	v_pk_mul_f32 v[126:127], v[8:9], v[122:123] op_sel:[1,0]
	s_nop 0
	v_pk_fma_f32 v[128:129], v[8:9], v[122:123], v[126:127] op_sel:[0,0,1] op_sel_hi:[1,1,0] neg_lo:[0,0,1] neg_hi:[0,0,1]
	v_pk_fma_f32 v[122:123], v[8:9], v[122:123], v[126:127] op_sel:[0,0,1] op_sel_hi:[0,1,0]
	v_mov_b32_e32 v129, v123
	v_pk_add_f32 v[120:121], v[128:129], v[120:121]
	v_lshl_add_u64 v[122:123], v[124:125], 0, s[18:19]
	v_cvt_pk_bf16_f32 v3, v120, v121
	global_store_short v[124:125], v3, off sc1
	global_store_short_d16_hi v[124:125], v3, off offset:128 sc1
	v_pk_mul_f32 v[124:125], v[8:9], v[120:121] op_sel:[1,0]
	s_nop 0
	v_pk_fma_f32 v[126:127], v[8:9], v[120:121], v[124:125] op_sel:[0,0,1] op_sel_hi:[1,1,0] neg_lo:[0,0,1] neg_hi:[0,0,1]
	v_pk_fma_f32 v[120:121], v[8:9], v[120:121], v[124:125] op_sel:[0,0,1] op_sel_hi:[0,1,0]
	v_mov_b32_e32 v127, v121
	v_pk_add_f32 v[118:119], v[126:127], v[118:119]
	v_lshl_add_u64 v[120:121], v[122:123], 0, s[18:19]
	v_cvt_pk_bf16_f32 v3, v118, v119
	global_store_short v[122:123], v3, off sc1
	global_store_short_d16_hi v[122:123], v3, off offset:128 sc1
	v_pk_mul_f32 v[122:123], v[8:9], v[118:119] op_sel:[1,0]
	s_nop 0
	v_pk_fma_f32 v[124:125], v[8:9], v[118:119], v[122:123] op_sel:[0,0,1] op_sel_hi:[1,1,0] neg_lo:[0,0,1] neg_hi:[0,0,1]
	v_pk_fma_f32 v[118:119], v[8:9], v[118:119], v[122:123] op_sel:[0,0,1] op_sel_hi:[0,1,0]
	v_mov_b32_e32 v125, v119
	v_pk_add_f32 v[116:117], v[124:125], v[116:117]
	v_lshl_add_u64 v[118:119], v[120:121], 0, s[18:19]
	v_cvt_pk_bf16_f32 v3, v116, v117
	global_store_short v[120:121], v3, off sc1
	global_store_short_d16_hi v[120:121], v3, off offset:128 sc1
	v_pk_mul_f32 v[120:121], v[8:9], v[116:117] op_sel:[1,0]
	s_nop 0
	v_pk_fma_f32 v[122:123], v[8:9], v[116:117], v[120:121] op_sel:[0,0,1] op_sel_hi:[1,1,0] neg_lo:[0,0,1] neg_hi:[0,0,1]
	v_pk_fma_f32 v[116:117], v[8:9], v[116:117], v[120:121] op_sel:[0,0,1] op_sel_hi:[0,1,0]
	v_mov_b32_e32 v123, v117
	v_pk_add_f32 v[114:115], v[122:123], v[114:115]
	v_lshl_add_u64 v[116:117], v[118:119], 0, s[18:19]
	v_cvt_pk_bf16_f32 v3, v114, v115
	global_store_short v[118:119], v3, off sc1
	global_store_short_d16_hi v[118:119], v3, off offset:128 sc1
	v_pk_mul_f32 v[118:119], v[8:9], v[114:115] op_sel:[1,0]
	s_nop 0
	v_pk_fma_f32 v[120:121], v[8:9], v[114:115], v[118:119] op_sel:[0,0,1] op_sel_hi:[1,1,0] neg_lo:[0,0,1] neg_hi:[0,0,1]
	v_pk_fma_f32 v[114:115], v[8:9], v[114:115], v[118:119] op_sel:[0,0,1] op_sel_hi:[0,1,0]
	v_mov_b32_e32 v121, v115
	v_pk_add_f32 v[112:113], v[120:121], v[112:113]
	v_lshl_add_u64 v[114:115], v[116:117], 0, s[18:19]
	v_cvt_pk_bf16_f32 v3, v112, v113
	global_store_short v[116:117], v3, off sc1
	global_store_short_d16_hi v[116:117], v3, off offset:128 sc1
	v_pk_mul_f32 v[116:117], v[8:9], v[112:113] op_sel:[1,0]
	s_nop 0
	v_pk_fma_f32 v[118:119], v[8:9], v[112:113], v[116:117] op_sel:[0,0,1] op_sel_hi:[1,1,0] neg_lo:[0,0,1] neg_hi:[0,0,1]
	v_pk_fma_f32 v[112:113], v[8:9], v[112:113], v[116:117] op_sel:[0,0,1] op_sel_hi:[0,1,0]
	v_mov_b32_e32 v119, v113
	v_pk_add_f32 v[110:111], v[118:119], v[110:111]
	v_lshl_add_u64 v[112:113], v[114:115], 0, s[18:19]
	v_cvt_pk_bf16_f32 v3, v110, v111
	global_store_short v[114:115], v3, off sc1
	global_store_short_d16_hi v[114:115], v3, off offset:128 sc1
	v_pk_mul_f32 v[114:115], v[8:9], v[110:111] op_sel:[1,0]
	s_nop 0
	v_pk_fma_f32 v[116:117], v[8:9], v[110:111], v[114:115] op_sel:[0,0,1] op_sel_hi:[1,1,0] neg_lo:[0,0,1] neg_hi:[0,0,1]
	v_pk_fma_f32 v[110:111], v[8:9], v[110:111], v[114:115] op_sel:[0,0,1] op_sel_hi:[0,1,0]
	v_mov_b32_e32 v117, v111
	v_pk_add_f32 v[108:109], v[116:117], v[108:109]
	v_lshl_add_u64 v[110:111], v[112:113], 0, s[18:19]
	v_cvt_pk_bf16_f32 v3, v108, v109
	global_store_short v[112:113], v3, off sc1
	global_store_short_d16_hi v[112:113], v3, off offset:128 sc1
	v_pk_mul_f32 v[112:113], v[8:9], v[108:109] op_sel:[1,0]
	s_nop 0
	v_pk_fma_f32 v[114:115], v[8:9], v[108:109], v[112:113] op_sel:[0,0,1] op_sel_hi:[1,1,0] neg_lo:[0,0,1] neg_hi:[0,0,1]
	v_pk_fma_f32 v[108:109], v[8:9], v[108:109], v[112:113] op_sel:[0,0,1] op_sel_hi:[0,1,0]
	v_mov_b32_e32 v115, v109
	v_pk_add_f32 v[106:107], v[114:115], v[106:107]
	v_lshl_add_u64 v[108:109], v[110:111], 0, s[18:19]
	v_cvt_pk_bf16_f32 v3, v106, v107
	global_store_short v[110:111], v3, off sc1
	global_store_short_d16_hi v[110:111], v3, off offset:128 sc1
	v_pk_mul_f32 v[110:111], v[8:9], v[106:107] op_sel:[1,0]
	s_nop 0
	v_pk_fma_f32 v[112:113], v[8:9], v[106:107], v[110:111] op_sel:[0,0,1] op_sel_hi:[1,1,0] neg_lo:[0,0,1] neg_hi:[0,0,1]
	v_pk_fma_f32 v[106:107], v[8:9], v[106:107], v[110:111] op_sel:[0,0,1] op_sel_hi:[0,1,0]
	v_mov_b32_e32 v113, v107
	v_pk_add_f32 v[104:105], v[112:113], v[104:105]
	v_lshl_add_u64 v[106:107], v[108:109], 0, s[18:19]
	v_cvt_pk_bf16_f32 v3, v104, v105
	global_store_short v[108:109], v3, off sc1
	global_store_short_d16_hi v[108:109], v3, off offset:128 sc1
	v_pk_mul_f32 v[108:109], v[8:9], v[104:105] op_sel:[1,0]
	s_nop 0
	v_pk_fma_f32 v[110:111], v[8:9], v[104:105], v[108:109] op_sel:[0,0,1] op_sel_hi:[1,1,0] neg_lo:[0,0,1] neg_hi:[0,0,1]
	v_pk_fma_f32 v[104:105], v[8:9], v[104:105], v[108:109] op_sel:[0,0,1] op_sel_hi:[0,1,0]
	v_mov_b32_e32 v111, v105
	v_pk_add_f32 v[102:103], v[110:111], v[102:103]
	v_lshl_add_u64 v[104:105], v[106:107], 0, s[18:19]
	v_cvt_pk_bf16_f32 v3, v102, v103
	global_store_short v[106:107], v3, off sc1
	global_store_short_d16_hi v[106:107], v3, off offset:128 sc1
	v_pk_mul_f32 v[106:107], v[8:9], v[102:103] op_sel:[1,0]
	s_nop 0
	v_pk_fma_f32 v[108:109], v[8:9], v[102:103], v[106:107] op_sel:[0,0,1] op_sel_hi:[1,1,0] neg_lo:[0,0,1] neg_hi:[0,0,1]
	v_pk_fma_f32 v[102:103], v[8:9], v[102:103], v[106:107] op_sel:[0,0,1] op_sel_hi:[0,1,0]
	v_mov_b32_e32 v109, v103
	v_pk_add_f32 v[100:101], v[108:109], v[100:101]
	v_lshl_add_u64 v[102:103], v[104:105], 0, s[18:19]
	v_cvt_pk_bf16_f32 v3, v100, v101
	global_store_short v[104:105], v3, off sc1
	global_store_short_d16_hi v[104:105], v3, off offset:128 sc1
	v_pk_mul_f32 v[104:105], v[8:9], v[100:101] op_sel:[1,0]
	s_nop 0
	v_pk_fma_f32 v[106:107], v[8:9], v[100:101], v[104:105] op_sel:[0,0,1] op_sel_hi:[1,1,0] neg_lo:[0,0,1] neg_hi:[0,0,1]
	v_pk_fma_f32 v[100:101], v[8:9], v[100:101], v[104:105] op_sel:[0,0,1] op_sel_hi:[0,1,0]
	v_mov_b32_e32 v107, v101
	v_pk_add_f32 v[98:99], v[106:107], v[98:99]
	v_lshl_add_u64 v[100:101], v[102:103], 0, s[18:19]
	v_cvt_pk_bf16_f32 v3, v98, v99
	global_store_short v[102:103], v3, off sc1
	global_store_short_d16_hi v[102:103], v3, off offset:128 sc1
	v_pk_mul_f32 v[102:103], v[8:9], v[98:99] op_sel:[1,0]
	s_nop 0
	v_pk_fma_f32 v[104:105], v[8:9], v[98:99], v[102:103] op_sel:[0,0,1] op_sel_hi:[1,1,0] neg_lo:[0,0,1] neg_hi:[0,0,1]
	v_pk_fma_f32 v[98:99], v[8:9], v[98:99], v[102:103] op_sel:[0,0,1] op_sel_hi:[0,1,0]
	v_mov_b32_e32 v105, v99
	v_pk_add_f32 v[96:97], v[104:105], v[96:97]
	v_lshl_add_u64 v[98:99], v[100:101], 0, s[18:19]
	v_cvt_pk_bf16_f32 v3, v96, v97
	global_store_short v[100:101], v3, off sc1
	global_store_short_d16_hi v[100:101], v3, off offset:128 sc1
	v_pk_mul_f32 v[100:101], v[8:9], v[96:97] op_sel:[1,0]
	s_nop 0
	v_pk_fma_f32 v[102:103], v[8:9], v[96:97], v[100:101] op_sel:[0,0,1] op_sel_hi:[1,1,0] neg_lo:[0,0,1] neg_hi:[0,0,1]
	v_pk_fma_f32 v[96:97], v[8:9], v[96:97], v[100:101] op_sel:[0,0,1] op_sel_hi:[0,1,0]
	v_mov_b32_e32 v103, v97
	v_pk_add_f32 v[94:95], v[102:103], v[94:95]
	v_lshl_add_u64 v[96:97], v[98:99], 0, s[18:19]
	v_cvt_pk_bf16_f32 v3, v94, v95
	global_store_short v[98:99], v3, off sc1
	global_store_short_d16_hi v[98:99], v3, off offset:128 sc1
	v_pk_mul_f32 v[98:99], v[8:9], v[94:95] op_sel:[1,0]
	s_nop 0
	v_pk_fma_f32 v[100:101], v[8:9], v[94:95], v[98:99] op_sel:[0,0,1] op_sel_hi:[1,1,0] neg_lo:[0,0,1] neg_hi:[0,0,1]
	v_pk_fma_f32 v[94:95], v[8:9], v[94:95], v[98:99] op_sel:[0,0,1] op_sel_hi:[0,1,0]
	v_mov_b32_e32 v101, v95
	v_pk_add_f32 v[92:93], v[100:101], v[92:93]
	v_lshl_add_u64 v[94:95], v[96:97], 0, s[18:19]
	v_cvt_pk_bf16_f32 v3, v92, v93
	global_store_short v[96:97], v3, off sc1
	global_store_short_d16_hi v[96:97], v3, off offset:128 sc1
	v_pk_mul_f32 v[96:97], v[8:9], v[92:93] op_sel:[1,0]
	s_nop 0
	v_pk_fma_f32 v[98:99], v[8:9], v[92:93], v[96:97] op_sel:[0,0,1] op_sel_hi:[1,1,0] neg_lo:[0,0,1] neg_hi:[0,0,1]
	v_pk_fma_f32 v[92:93], v[8:9], v[92:93], v[96:97] op_sel:[0,0,1] op_sel_hi:[0,1,0]
	v_mov_b32_e32 v99, v93
	v_pk_add_f32 v[90:91], v[98:99], v[90:91]
	v_lshl_add_u64 v[92:93], v[94:95], 0, s[18:19]
	v_cvt_pk_bf16_f32 v3, v90, v91
	global_store_short v[94:95], v3, off sc1
	global_store_short_d16_hi v[94:95], v3, off offset:128 sc1
	v_pk_mul_f32 v[94:95], v[8:9], v[90:91] op_sel:[1,0]
	s_nop 0
	v_pk_fma_f32 v[96:97], v[8:9], v[90:91], v[94:95] op_sel:[0,0,1] op_sel_hi:[1,1,0] neg_lo:[0,0,1] neg_hi:[0,0,1]
	v_pk_fma_f32 v[90:91], v[8:9], v[90:91], v[94:95] op_sel:[0,0,1] op_sel_hi:[0,1,0]
	v_mov_b32_e32 v97, v91
	v_pk_add_f32 v[88:89], v[96:97], v[88:89]
	v_lshl_add_u64 v[90:91], v[92:93], 0, s[18:19]
	v_cvt_pk_bf16_f32 v3, v88, v89
	global_store_short v[92:93], v3, off sc1
	global_store_short_d16_hi v[92:93], v3, off offset:128 sc1
	v_pk_mul_f32 v[92:93], v[8:9], v[88:89] op_sel:[1,0]
	s_nop 0
	v_pk_fma_f32 v[94:95], v[8:9], v[88:89], v[92:93] op_sel:[0,0,1] op_sel_hi:[1,1,0] neg_lo:[0,0,1] neg_hi:[0,0,1]
	v_pk_fma_f32 v[88:89], v[8:9], v[88:89], v[92:93] op_sel:[0,0,1] op_sel_hi:[0,1,0]
	v_mov_b32_e32 v95, v89
	v_pk_add_f32 v[86:87], v[94:95], v[86:87]
	v_lshl_add_u64 v[88:89], v[90:91], 0, s[18:19]
	v_cvt_pk_bf16_f32 v3, v86, v87
	global_store_short v[90:91], v3, off sc1
	global_store_short_d16_hi v[90:91], v3, off offset:128 sc1
	v_pk_mul_f32 v[90:91], v[8:9], v[86:87] op_sel:[1,0]
	s_nop 0
	v_pk_fma_f32 v[92:93], v[8:9], v[86:87], v[90:91] op_sel:[0,0,1] op_sel_hi:[1,1,0] neg_lo:[0,0,1] neg_hi:[0,0,1]
	v_pk_fma_f32 v[86:87], v[8:9], v[86:87], v[90:91] op_sel:[0,0,1] op_sel_hi:[0,1,0]
	v_mov_b32_e32 v93, v87
	v_pk_add_f32 v[84:85], v[92:93], v[84:85]
	v_lshl_add_u64 v[86:87], v[88:89], 0, s[18:19]
	v_cvt_pk_bf16_f32 v3, v84, v85
	global_store_short v[88:89], v3, off sc1
	global_store_short_d16_hi v[88:89], v3, off offset:128 sc1
	v_pk_mul_f32 v[88:89], v[8:9], v[84:85] op_sel:[1,0]
	s_nop 0
	v_pk_fma_f32 v[90:91], v[8:9], v[84:85], v[88:89] op_sel:[0,0,1] op_sel_hi:[1,1,0] neg_lo:[0,0,1] neg_hi:[0,0,1]
	v_pk_fma_f32 v[84:85], v[8:9], v[84:85], v[88:89] op_sel:[0,0,1] op_sel_hi:[0,1,0]
	v_mov_b32_e32 v91, v85
	v_pk_add_f32 v[82:83], v[90:91], v[82:83]
	v_lshl_add_u64 v[84:85], v[86:87], 0, s[18:19]
	v_cvt_pk_bf16_f32 v3, v82, v83
	global_store_short v[86:87], v3, off sc1
	global_store_short_d16_hi v[86:87], v3, off offset:128 sc1
	v_pk_mul_f32 v[86:87], v[8:9], v[82:83] op_sel:[1,0]
	s_nop 0
	v_pk_fma_f32 v[88:89], v[8:9], v[82:83], v[86:87] op_sel:[0,0,1] op_sel_hi:[1,1,0] neg_lo:[0,0,1] neg_hi:[0,0,1]
	v_pk_fma_f32 v[82:83], v[8:9], v[82:83], v[86:87] op_sel:[0,0,1] op_sel_hi:[0,1,0]
	v_mov_b32_e32 v89, v83
	v_pk_add_f32 v[80:81], v[88:89], v[80:81]
	v_lshl_add_u64 v[82:83], v[84:85], 0, s[18:19]
	v_cvt_pk_bf16_f32 v3, v80, v81
	global_store_short v[84:85], v3, off sc1
	global_store_short_d16_hi v[84:85], v3, off offset:128 sc1
	v_pk_mul_f32 v[84:85], v[8:9], v[80:81] op_sel:[1,0]
	s_nop 0
	v_pk_fma_f32 v[86:87], v[8:9], v[80:81], v[84:85] op_sel:[0,0,1] op_sel_hi:[1,1,0] neg_lo:[0,0,1] neg_hi:[0,0,1]
	v_pk_fma_f32 v[80:81], v[8:9], v[80:81], v[84:85] op_sel:[0,0,1] op_sel_hi:[0,1,0]
	v_mov_b32_e32 v87, v81
	v_pk_add_f32 v[78:79], v[86:87], v[78:79]
	v_lshl_add_u64 v[80:81], v[82:83], 0, s[18:19]
	v_cvt_pk_bf16_f32 v3, v78, v79
	global_store_short v[82:83], v3, off sc1
	global_store_short_d16_hi v[82:83], v3, off offset:128 sc1
	v_pk_mul_f32 v[82:83], v[8:9], v[78:79] op_sel:[1,0]
	s_nop 0
	v_pk_fma_f32 v[84:85], v[8:9], v[78:79], v[82:83] op_sel:[0,0,1] op_sel_hi:[1,1,0] neg_lo:[0,0,1] neg_hi:[0,0,1]
	v_pk_fma_f32 v[78:79], v[8:9], v[78:79], v[82:83] op_sel:[0,0,1] op_sel_hi:[0,1,0]
	v_mov_b32_e32 v85, v79
	v_pk_add_f32 v[76:77], v[84:85], v[76:77]
	v_lshl_add_u64 v[78:79], v[80:81], 0, s[18:19]
	v_cvt_pk_bf16_f32 v3, v76, v77
	global_store_short v[80:81], v3, off sc1
	global_store_short_d16_hi v[80:81], v3, off offset:128 sc1
	v_pk_mul_f32 v[80:81], v[8:9], v[76:77] op_sel:[1,0]
	s_nop 0
	v_pk_fma_f32 v[82:83], v[8:9], v[76:77], v[80:81] op_sel:[0,0,1] op_sel_hi:[1,1,0] neg_lo:[0,0,1] neg_hi:[0,0,1]
	v_pk_fma_f32 v[76:77], v[8:9], v[76:77], v[80:81] op_sel:[0,0,1] op_sel_hi:[0,1,0]
	v_mov_b32_e32 v83, v77
	v_pk_add_f32 v[74:75], v[82:83], v[74:75]
	v_lshl_add_u64 v[76:77], v[78:79], 0, s[18:19]
	v_cvt_pk_bf16_f32 v3, v74, v75
	global_store_short v[78:79], v3, off sc1
	global_store_short_d16_hi v[78:79], v3, off offset:128 sc1
	v_pk_mul_f32 v[78:79], v[8:9], v[74:75] op_sel:[1,0]
	s_nop 0
	v_pk_fma_f32 v[80:81], v[8:9], v[74:75], v[78:79] op_sel:[0,0,1] op_sel_hi:[1,1,0] neg_lo:[0,0,1] neg_hi:[0,0,1]
	v_pk_fma_f32 v[74:75], v[8:9], v[74:75], v[78:79] op_sel:[0,0,1] op_sel_hi:[0,1,0]
	v_mov_b32_e32 v81, v75
	v_pk_add_f32 v[72:73], v[80:81], v[72:73]
	v_lshl_add_u64 v[74:75], v[76:77], 0, s[18:19]
	v_cvt_pk_bf16_f32 v3, v72, v73
	global_store_short v[76:77], v3, off sc1
	global_store_short_d16_hi v[76:77], v3, off offset:128 sc1
	v_pk_mul_f32 v[76:77], v[8:9], v[72:73] op_sel:[1,0]
	s_nop 0
	v_pk_fma_f32 v[78:79], v[8:9], v[72:73], v[76:77] op_sel:[0,0,1] op_sel_hi:[1,1,0] neg_lo:[0,0,1] neg_hi:[0,0,1]
	v_pk_fma_f32 v[72:73], v[8:9], v[72:73], v[76:77] op_sel:[0,0,1] op_sel_hi:[0,1,0]
	v_mov_b32_e32 v79, v73
	v_pk_add_f32 v[70:71], v[78:79], v[70:71]
	v_lshl_add_u64 v[72:73], v[74:75], 0, s[18:19]
	v_cvt_pk_bf16_f32 v3, v70, v71
	global_store_short v[74:75], v3, off sc1
	global_store_short_d16_hi v[74:75], v3, off offset:128 sc1
	v_pk_mul_f32 v[74:75], v[8:9], v[70:71] op_sel:[1,0]
	s_nop 0
	v_pk_fma_f32 v[76:77], v[8:9], v[70:71], v[74:75] op_sel:[0,0,1] op_sel_hi:[1,1,0] neg_lo:[0,0,1] neg_hi:[0,0,1]
	v_pk_fma_f32 v[70:71], v[8:9], v[70:71], v[74:75] op_sel:[0,0,1] op_sel_hi:[0,1,0]
	v_mov_b32_e32 v77, v71
	v_pk_add_f32 v[68:69], v[76:77], v[68:69]
	v_lshl_add_u64 v[70:71], v[72:73], 0, s[18:19]
	v_cvt_pk_bf16_f32 v3, v68, v69
	global_store_short v[72:73], v3, off sc1
	global_store_short_d16_hi v[72:73], v3, off offset:128 sc1
	v_pk_mul_f32 v[72:73], v[8:9], v[68:69] op_sel:[1,0]
	s_nop 0
	v_pk_fma_f32 v[74:75], v[8:9], v[68:69], v[72:73] op_sel:[0,0,1] op_sel_hi:[1,1,0] neg_lo:[0,0,1] neg_hi:[0,0,1]
	v_pk_fma_f32 v[68:69], v[8:9], v[68:69], v[72:73] op_sel:[0,0,1] op_sel_hi:[0,1,0]
	v_mov_b32_e32 v75, v69
	v_pk_add_f32 v[66:67], v[74:75], v[66:67]
	v_lshl_add_u64 v[68:69], v[70:71], 0, s[18:19]
	v_cvt_pk_bf16_f32 v3, v66, v67
	global_store_short v[70:71], v3, off sc1
	global_store_short_d16_hi v[70:71], v3, off offset:128 sc1
	v_pk_mul_f32 v[70:71], v[8:9], v[66:67] op_sel:[1,0]
	s_nop 0
	v_pk_fma_f32 v[72:73], v[8:9], v[66:67], v[70:71] op_sel:[0,0,1] op_sel_hi:[1,1,0] neg_lo:[0,0,1] neg_hi:[0,0,1]
	v_pk_fma_f32 v[66:67], v[8:9], v[66:67], v[70:71] op_sel:[0,0,1] op_sel_hi:[0,1,0]
	v_mov_b32_e32 v73, v67
	v_pk_add_f32 v[64:65], v[72:73], v[64:65]
	v_lshl_add_u64 v[66:67], v[68:69], 0, s[18:19]
	v_cvt_pk_bf16_f32 v3, v64, v65
	global_store_short v[68:69], v3, off sc1
	global_store_short_d16_hi v[68:69], v3, off offset:128 sc1
	v_pk_mul_f32 v[68:69], v[8:9], v[64:65] op_sel:[1,0]
	s_nop 0
	v_pk_fma_f32 v[70:71], v[8:9], v[64:65], v[68:69] op_sel:[0,0,1] op_sel_hi:[1,1,0] neg_lo:[0,0,1] neg_hi:[0,0,1]
	v_pk_fma_f32 v[64:65], v[8:9], v[64:65], v[68:69] op_sel:[0,0,1] op_sel_hi:[0,1,0]
	v_mov_b32_e32 v71, v65
	v_pk_add_f32 v[62:63], v[70:71], v[62:63]
	v_lshl_add_u64 v[64:65], v[66:67], 0, s[18:19]
	v_cvt_pk_bf16_f32 v3, v62, v63
	global_store_short v[66:67], v3, off sc1
	global_store_short_d16_hi v[66:67], v3, off offset:128 sc1
	v_pk_mul_f32 v[66:67], v[8:9], v[62:63] op_sel:[1,0]
	s_nop 0
	v_pk_fma_f32 v[68:69], v[8:9], v[62:63], v[66:67] op_sel:[0,0,1] op_sel_hi:[1,1,0] neg_lo:[0,0,1] neg_hi:[0,0,1]
	v_pk_fma_f32 v[62:63], v[8:9], v[62:63], v[66:67] op_sel:[0,0,1] op_sel_hi:[0,1,0]
	v_mov_b32_e32 v69, v63
	v_pk_add_f32 v[60:61], v[68:69], v[60:61]
	v_lshl_add_u64 v[62:63], v[64:65], 0, s[18:19]
	v_cvt_pk_bf16_f32 v3, v60, v61
	global_store_short v[64:65], v3, off sc1
	global_store_short_d16_hi v[64:65], v3, off offset:128 sc1
	v_pk_mul_f32 v[64:65], v[8:9], v[60:61] op_sel:[1,0]
	s_nop 0
	v_pk_fma_f32 v[66:67], v[8:9], v[60:61], v[64:65] op_sel:[0,0,1] op_sel_hi:[1,1,0] neg_lo:[0,0,1] neg_hi:[0,0,1]
	v_pk_fma_f32 v[60:61], v[8:9], v[60:61], v[64:65] op_sel:[0,0,1] op_sel_hi:[0,1,0]
	v_mov_b32_e32 v67, v61
	v_pk_add_f32 v[58:59], v[66:67], v[58:59]
	v_lshl_add_u64 v[60:61], v[62:63], 0, s[18:19]
	v_cvt_pk_bf16_f32 v3, v58, v59
	global_store_short v[62:63], v3, off sc1
	global_store_short_d16_hi v[62:63], v3, off offset:128 sc1
	v_pk_mul_f32 v[62:63], v[8:9], v[58:59] op_sel:[1,0]
	s_nop 0
	v_pk_fma_f32 v[64:65], v[8:9], v[58:59], v[62:63] op_sel:[0,0,1] op_sel_hi:[1,1,0] neg_lo:[0,0,1] neg_hi:[0,0,1]
	v_pk_fma_f32 v[58:59], v[8:9], v[58:59], v[62:63] op_sel:[0,0,1] op_sel_hi:[0,1,0]
	v_mov_b32_e32 v65, v59
	v_pk_add_f32 v[56:57], v[64:65], v[56:57]
	v_lshl_add_u64 v[58:59], v[60:61], 0, s[18:19]
	v_cvt_pk_bf16_f32 v3, v56, v57
	global_store_short v[60:61], v3, off sc1
	global_store_short_d16_hi v[60:61], v3, off offset:128 sc1
	v_pk_mul_f32 v[60:61], v[8:9], v[56:57] op_sel:[1,0]
	s_nop 0
	v_pk_fma_f32 v[62:63], v[8:9], v[56:57], v[60:61] op_sel:[0,0,1] op_sel_hi:[1,1,0] neg_lo:[0,0,1] neg_hi:[0,0,1]
	v_pk_fma_f32 v[56:57], v[8:9], v[56:57], v[60:61] op_sel:[0,0,1] op_sel_hi:[0,1,0]
	v_mov_b32_e32 v63, v57
	v_pk_add_f32 v[54:55], v[62:63], v[54:55]
	v_lshl_add_u64 v[56:57], v[58:59], 0, s[18:19]
	v_cvt_pk_bf16_f32 v3, v54, v55
	global_store_short v[58:59], v3, off sc1
	global_store_short_d16_hi v[58:59], v3, off offset:128 sc1
	v_pk_mul_f32 v[58:59], v[8:9], v[54:55] op_sel:[1,0]
	s_nop 0
	v_pk_fma_f32 v[60:61], v[8:9], v[54:55], v[58:59] op_sel:[0,0,1] op_sel_hi:[1,1,0] neg_lo:[0,0,1] neg_hi:[0,0,1]
	v_pk_fma_f32 v[54:55], v[8:9], v[54:55], v[58:59] op_sel:[0,0,1] op_sel_hi:[0,1,0]
	v_mov_b32_e32 v61, v55
	v_pk_add_f32 v[52:53], v[60:61], v[52:53]
	v_lshl_add_u64 v[54:55], v[56:57], 0, s[18:19]
	v_cvt_pk_bf16_f32 v3, v52, v53
	global_store_short v[56:57], v3, off sc1
	global_store_short_d16_hi v[56:57], v3, off offset:128 sc1
	v_pk_mul_f32 v[56:57], v[8:9], v[52:53] op_sel:[1,0]
	s_nop 0
	v_pk_fma_f32 v[58:59], v[8:9], v[52:53], v[56:57] op_sel:[0,0,1] op_sel_hi:[1,1,0] neg_lo:[0,0,1] neg_hi:[0,0,1]
	v_pk_fma_f32 v[52:53], v[8:9], v[52:53], v[56:57] op_sel:[0,0,1] op_sel_hi:[0,1,0]
	v_mov_b32_e32 v59, v53
	v_pk_add_f32 v[50:51], v[58:59], v[50:51]
	v_lshl_add_u64 v[52:53], v[54:55], 0, s[18:19]
	v_cvt_pk_bf16_f32 v3, v50, v51
	global_store_short v[54:55], v3, off sc1
	global_store_short_d16_hi v[54:55], v3, off offset:128 sc1
	v_pk_mul_f32 v[54:55], v[8:9], v[50:51] op_sel:[1,0]
	s_nop 0
	v_pk_fma_f32 v[56:57], v[8:9], v[50:51], v[54:55] op_sel:[0,0,1] op_sel_hi:[1,1,0] neg_lo:[0,0,1] neg_hi:[0,0,1]
	v_pk_fma_f32 v[50:51], v[8:9], v[50:51], v[54:55] op_sel:[0,0,1] op_sel_hi:[0,1,0]
	v_mov_b32_e32 v57, v51
	v_pk_add_f32 v[48:49], v[56:57], v[48:49]
	v_lshl_add_u64 v[50:51], v[52:53], 0, s[18:19]
	v_cvt_pk_bf16_f32 v3, v48, v49
	global_store_short v[52:53], v3, off sc1
	global_store_short_d16_hi v[52:53], v3, off offset:128 sc1
	v_pk_mul_f32 v[52:53], v[8:9], v[48:49] op_sel:[1,0]
	s_nop 0
	v_pk_fma_f32 v[54:55], v[8:9], v[48:49], v[52:53] op_sel:[0,0,1] op_sel_hi:[1,1,0] neg_lo:[0,0,1] neg_hi:[0,0,1]
	v_pk_fma_f32 v[48:49], v[8:9], v[48:49], v[52:53] op_sel:[0,0,1] op_sel_hi:[0,1,0]
	v_mov_b32_e32 v55, v49
	v_pk_add_f32 v[46:47], v[54:55], v[46:47]
	v_lshl_add_u64 v[48:49], v[50:51], 0, s[18:19]
	v_cvt_pk_bf16_f32 v3, v46, v47
	global_store_short v[50:51], v3, off sc1
	global_store_short_d16_hi v[50:51], v3, off offset:128 sc1
	v_pk_mul_f32 v[50:51], v[8:9], v[46:47] op_sel:[1,0]
	s_nop 0
	v_pk_fma_f32 v[52:53], v[8:9], v[46:47], v[50:51] op_sel:[0,0,1] op_sel_hi:[1,1,0] neg_lo:[0,0,1] neg_hi:[0,0,1]
	v_pk_fma_f32 v[46:47], v[8:9], v[46:47], v[50:51] op_sel:[0,0,1] op_sel_hi:[0,1,0]
	v_mov_b32_e32 v53, v47
	v_pk_add_f32 v[44:45], v[52:53], v[44:45]
	v_lshl_add_u64 v[46:47], v[48:49], 0, s[18:19]
	v_cvt_pk_bf16_f32 v3, v44, v45
	global_store_short v[48:49], v3, off sc1
	global_store_short_d16_hi v[48:49], v3, off offset:128 sc1
	v_pk_mul_f32 v[48:49], v[8:9], v[44:45] op_sel:[1,0]
	s_nop 0
	v_pk_fma_f32 v[50:51], v[8:9], v[44:45], v[48:49] op_sel:[0,0,1] op_sel_hi:[1,1,0] neg_lo:[0,0,1] neg_hi:[0,0,1]
	v_pk_fma_f32 v[44:45], v[8:9], v[44:45], v[48:49] op_sel:[0,0,1] op_sel_hi:[0,1,0]
	v_mov_b32_e32 v51, v45
	v_pk_add_f32 v[42:43], v[50:51], v[42:43]
	v_lshl_add_u64 v[44:45], v[46:47], 0, s[18:19]
	v_cvt_pk_bf16_f32 v3, v42, v43
	global_store_short v[46:47], v3, off sc1
	global_store_short_d16_hi v[46:47], v3, off offset:128 sc1
	v_pk_mul_f32 v[46:47], v[8:9], v[42:43] op_sel:[1,0]
	s_nop 0
	v_pk_fma_f32 v[48:49], v[8:9], v[42:43], v[46:47] op_sel:[0,0,1] op_sel_hi:[1,1,0] neg_lo:[0,0,1] neg_hi:[0,0,1]
	v_pk_fma_f32 v[42:43], v[8:9], v[42:43], v[46:47] op_sel:[0,0,1] op_sel_hi:[0,1,0]
	v_mov_b32_e32 v49, v43
	v_pk_add_f32 v[40:41], v[48:49], v[40:41]
	v_lshl_add_u64 v[42:43], v[44:45], 0, s[18:19]
	v_cvt_pk_bf16_f32 v3, v40, v41
	global_store_short v[44:45], v3, off sc1
	global_store_short_d16_hi v[44:45], v3, off offset:128 sc1
	v_pk_mul_f32 v[44:45], v[8:9], v[40:41] op_sel:[1,0]
	s_nop 0
	v_pk_fma_f32 v[46:47], v[8:9], v[40:41], v[44:45] op_sel:[0,0,1] op_sel_hi:[1,1,0] neg_lo:[0,0,1] neg_hi:[0,0,1]
	v_pk_fma_f32 v[40:41], v[8:9], v[40:41], v[44:45] op_sel:[0,0,1] op_sel_hi:[0,1,0]
	v_mov_b32_e32 v47, v41
	v_pk_add_f32 v[38:39], v[46:47], v[38:39]
	v_lshl_add_u64 v[40:41], v[42:43], 0, s[18:19]
	v_cvt_pk_bf16_f32 v3, v38, v39
	global_store_short v[42:43], v3, off sc1
	global_store_short_d16_hi v[42:43], v3, off offset:128 sc1
	v_pk_mul_f32 v[42:43], v[8:9], v[38:39] op_sel:[1,0]
	s_nop 0
	v_pk_fma_f32 v[44:45], v[8:9], v[38:39], v[42:43] op_sel:[0,0,1] op_sel_hi:[1,1,0] neg_lo:[0,0,1] neg_hi:[0,0,1]
	v_pk_fma_f32 v[38:39], v[8:9], v[38:39], v[42:43] op_sel:[0,0,1] op_sel_hi:[0,1,0]
	v_mov_b32_e32 v45, v39
	v_pk_add_f32 v[36:37], v[44:45], v[36:37]
	v_lshl_add_u64 v[38:39], v[40:41], 0, s[18:19]
	v_cvt_pk_bf16_f32 v3, v36, v37
	global_store_short v[40:41], v3, off sc1
	global_store_short_d16_hi v[40:41], v3, off offset:128 sc1
	v_pk_mul_f32 v[40:41], v[8:9], v[36:37] op_sel:[1,0]
	s_nop 0
	v_pk_fma_f32 v[42:43], v[8:9], v[36:37], v[40:41] op_sel:[0,0,1] op_sel_hi:[1,1,0] neg_lo:[0,0,1] neg_hi:[0,0,1]
	v_pk_fma_f32 v[36:37], v[8:9], v[36:37], v[40:41] op_sel:[0,0,1] op_sel_hi:[0,1,0]
	v_mov_b32_e32 v43, v37
	v_pk_add_f32 v[34:35], v[42:43], v[34:35]
	v_lshl_add_u64 v[36:37], v[38:39], 0, s[18:19]
	v_cvt_pk_bf16_f32 v3, v34, v35
	global_store_short v[38:39], v3, off sc1
	global_store_short_d16_hi v[38:39], v3, off offset:128 sc1
	v_pk_mul_f32 v[38:39], v[8:9], v[34:35] op_sel:[1,0]
	s_nop 0
	v_pk_fma_f32 v[40:41], v[8:9], v[34:35], v[38:39] op_sel:[0,0,1] op_sel_hi:[1,1,0] neg_lo:[0,0,1] neg_hi:[0,0,1]
	v_pk_fma_f32 v[34:35], v[8:9], v[34:35], v[38:39] op_sel:[0,0,1] op_sel_hi:[0,1,0]
	v_mov_b32_e32 v41, v35
	v_pk_add_f32 v[32:33], v[40:41], v[32:33]
	v_lshl_add_u64 v[34:35], v[36:37], 0, s[18:19]
	v_cvt_pk_bf16_f32 v3, v32, v33
	global_store_short v[36:37], v3, off sc1
	global_store_short_d16_hi v[36:37], v3, off offset:128 sc1
	v_pk_mul_f32 v[36:37], v[8:9], v[32:33] op_sel:[1,0]
	s_nop 0
	v_pk_fma_f32 v[38:39], v[8:9], v[32:33], v[36:37] op_sel:[0,0,1] op_sel_hi:[1,1,0] neg_lo:[0,0,1] neg_hi:[0,0,1]
	v_pk_fma_f32 v[32:33], v[8:9], v[32:33], v[36:37] op_sel:[0,0,1] op_sel_hi:[0,1,0]
	v_mov_b32_e32 v39, v33
	v_pk_add_f32 v[30:31], v[38:39], v[30:31]
	v_lshl_add_u64 v[32:33], v[34:35], 0, s[18:19]
	v_cvt_pk_bf16_f32 v3, v30, v31
	global_store_short v[34:35], v3, off sc1
	global_store_short_d16_hi v[34:35], v3, off offset:128 sc1
	v_pk_mul_f32 v[34:35], v[8:9], v[30:31] op_sel:[1,0]
	s_nop 0
	v_pk_fma_f32 v[36:37], v[8:9], v[30:31], v[34:35] op_sel:[0,0,1] op_sel_hi:[1,1,0] neg_lo:[0,0,1] neg_hi:[0,0,1]
	v_pk_fma_f32 v[30:31], v[8:9], v[30:31], v[34:35] op_sel:[0,0,1] op_sel_hi:[0,1,0]
	v_mov_b32_e32 v37, v31
	v_pk_add_f32 v[28:29], v[36:37], v[28:29]
	v_lshl_add_u64 v[30:31], v[32:33], 0, s[18:19]
	v_cvt_pk_bf16_f32 v3, v28, v29
	global_store_short v[32:33], v3, off sc1
	global_store_short_d16_hi v[32:33], v3, off offset:128 sc1
	v_pk_mul_f32 v[32:33], v[8:9], v[28:29] op_sel:[1,0]
	s_nop 0
	v_pk_fma_f32 v[34:35], v[8:9], v[28:29], v[32:33] op_sel:[0,0,1] op_sel_hi:[1,1,0] neg_lo:[0,0,1] neg_hi:[0,0,1]
	v_pk_fma_f32 v[28:29], v[8:9], v[28:29], v[32:33] op_sel:[0,0,1] op_sel_hi:[0,1,0]
	v_mov_b32_e32 v35, v29
	v_pk_add_f32 v[26:27], v[34:35], v[26:27]
	v_lshl_add_u64 v[28:29], v[30:31], 0, s[18:19]
	v_cvt_pk_bf16_f32 v3, v26, v27
	global_store_short v[30:31], v3, off sc1
	global_store_short_d16_hi v[30:31], v3, off offset:128 sc1
	v_pk_mul_f32 v[30:31], v[8:9], v[26:27] op_sel:[1,0]
	s_nop 0
	v_pk_fma_f32 v[32:33], v[8:9], v[26:27], v[30:31] op_sel:[0,0,1] op_sel_hi:[1,1,0] neg_lo:[0,0,1] neg_hi:[0,0,1]
	v_pk_fma_f32 v[26:27], v[8:9], v[26:27], v[30:31] op_sel:[0,0,1] op_sel_hi:[0,1,0]
	v_mov_b32_e32 v33, v27
	v_pk_add_f32 v[24:25], v[32:33], v[24:25]
	v_lshl_add_u64 v[26:27], v[28:29], 0, s[18:19]
	v_cvt_pk_bf16_f32 v3, v24, v25
	global_store_short v[28:29], v3, off sc1
	global_store_short_d16_hi v[28:29], v3, off offset:128 sc1
	v_pk_mul_f32 v[28:29], v[8:9], v[24:25] op_sel:[1,0]
	s_nop 0
	v_pk_fma_f32 v[30:31], v[8:9], v[24:25], v[28:29] op_sel:[0,0,1] op_sel_hi:[1,1,0] neg_lo:[0,0,1] neg_hi:[0,0,1]
	v_pk_fma_f32 v[24:25], v[8:9], v[24:25], v[28:29] op_sel:[0,0,1] op_sel_hi:[0,1,0]
	v_mov_b32_e32 v31, v25
	v_pk_add_f32 v[22:23], v[30:31], v[22:23]
	v_lshl_add_u64 v[24:25], v[26:27], 0, s[18:19]
	v_cvt_pk_bf16_f32 v3, v22, v23
	global_store_short v[26:27], v3, off sc1
	global_store_short_d16_hi v[26:27], v3, off offset:128 sc1
	v_pk_mul_f32 v[26:27], v[8:9], v[22:23] op_sel:[1,0]
	s_nop 0
	v_pk_fma_f32 v[28:29], v[8:9], v[22:23], v[26:27] op_sel:[0,0,1] op_sel_hi:[1,1,0] neg_lo:[0,0,1] neg_hi:[0,0,1]
	v_pk_fma_f32 v[22:23], v[8:9], v[22:23], v[26:27] op_sel:[0,0,1] op_sel_hi:[0,1,0]
	v_mov_b32_e32 v29, v23
	v_pk_add_f32 v[20:21], v[28:29], v[20:21]
	v_lshl_add_u64 v[22:23], v[24:25], 0, s[18:19]
	v_cvt_pk_bf16_f32 v3, v20, v21
	global_store_short v[24:25], v3, off sc1
	global_store_short_d16_hi v[24:25], v3, off offset:128 sc1
	v_pk_mul_f32 v[24:25], v[8:9], v[20:21] op_sel:[1,0]
	s_nop 0
	v_pk_fma_f32 v[26:27], v[8:9], v[20:21], v[24:25] op_sel:[0,0,1] op_sel_hi:[1,1,0] neg_lo:[0,0,1] neg_hi:[0,0,1]
	v_pk_fma_f32 v[20:21], v[8:9], v[20:21], v[24:25] op_sel:[0,0,1] op_sel_hi:[0,1,0]
	v_mov_b32_e32 v27, v21
	v_pk_add_f32 v[18:19], v[26:27], v[18:19]
	v_lshl_add_u64 v[20:21], v[22:23], 0, s[18:19]
	v_cvt_pk_bf16_f32 v3, v18, v19
	global_store_short v[22:23], v3, off sc1
	global_store_short_d16_hi v[22:23], v3, off offset:128 sc1
	v_pk_mul_f32 v[22:23], v[8:9], v[18:19] op_sel:[1,0]
	s_nop 0
	v_pk_fma_f32 v[24:25], v[8:9], v[18:19], v[22:23] op_sel:[0,0,1] op_sel_hi:[1,1,0] neg_lo:[0,0,1] neg_hi:[0,0,1]
	v_pk_fma_f32 v[18:19], v[8:9], v[18:19], v[22:23] op_sel:[0,0,1] op_sel_hi:[0,1,0]
	v_mov_b32_e32 v25, v19
	v_pk_add_f32 v[16:17], v[24:25], v[16:17]
	v_lshl_add_u64 v[18:19], v[20:21], 0, s[18:19]
	v_cvt_pk_bf16_f32 v3, v16, v17
	global_store_short v[20:21], v3, off sc1
	global_store_short_d16_hi v[20:21], v3, off offset:128 sc1
	v_pk_mul_f32 v[20:21], v[8:9], v[16:17] op_sel:[1,0]
	s_nop 0
	v_pk_fma_f32 v[22:23], v[8:9], v[16:17], v[20:21] op_sel:[0,0,1] op_sel_hi:[1,1,0] neg_lo:[0,0,1] neg_hi:[0,0,1]
	v_pk_fma_f32 v[16:17], v[8:9], v[16:17], v[20:21] op_sel:[0,0,1] op_sel_hi:[0,1,0]
	v_mov_b32_e32 v23, v17
	v_pk_add_f32 v[14:15], v[22:23], v[14:15]
	v_lshl_add_u64 v[16:17], v[18:19], 0, s[18:19]
	v_cvt_pk_bf16_f32 v3, v14, v15
	global_store_short v[18:19], v3, off sc1
	global_store_short_d16_hi v[18:19], v3, off offset:128 sc1
	v_pk_mul_f32 v[18:19], v[8:9], v[14:15] op_sel:[1,0]
	s_nop 0
	v_pk_fma_f32 v[20:21], v[8:9], v[14:15], v[18:19] op_sel:[0,0,1] op_sel_hi:[1,1,0] neg_lo:[0,0,1] neg_hi:[0,0,1]
	v_pk_fma_f32 v[14:15], v[8:9], v[14:15], v[18:19] op_sel:[0,0,1] op_sel_hi:[0,1,0]
	v_mov_b32_e32 v21, v15
	v_pk_add_f32 v[12:13], v[20:21], v[12:13]
	v_lshl_add_u64 v[14:15], v[16:17], 0, s[18:19]
	v_cvt_pk_bf16_f32 v3, v12, v13
	global_store_short v[16:17], v3, off sc1
	global_store_short_d16_hi v[16:17], v3, off offset:128 sc1
	v_pk_mul_f32 v[16:17], v[8:9], v[12:13] op_sel:[1,0]
	s_nop 0
	v_pk_fma_f32 v[18:19], v[8:9], v[12:13], v[16:17] op_sel:[0,0,1] op_sel_hi:[1,1,0] neg_lo:[0,0,1] neg_hi:[0,0,1]
	v_pk_fma_f32 v[8:9], v[8:9], v[12:13], v[16:17] op_sel:[0,0,1] op_sel_hi:[0,1,0]
	v_mov_b32_e32 v19, v9
	v_pk_add_f32 v[8:9], v[18:19], v[10:11]
	s_nop 0
	v_cvt_pk_bf16_f32 v3, v8, v9
	global_store_short v[14:15], v3, off sc1
	global_store_short_d16_hi v[14:15], v3, off offset:128 sc1
	s_waitcnt vmcnt(63) expcnt(7) lgkmcnt(15)
	s_barrier
	s_cbranch_scc1 .LBB0_605

.LBB0_641:
	s_ashr_i32 s97, s96, 31
	s_lshl_b64 s[26:27], s[96:97], 1
	s_add_u32 s24, s24, s26
	s_addc_u32 s25, s25, s27
	v_lshlrev_b32_e32 v2, 1, v2
	v_mov_b32_e32 v3, 0
	v_lshl_add_u64 v[2:3], s[24:25], 0, v[2:3]
	s_mov_b32 s24, 0x5040100
	s_waitcnt lgkmcnt(3)
	v_perm_b32 v14, v5, v4, s24
	s_waitcnt lgkmcnt(2)
	v_perm_b32 v15, v7, v6, s24
	s_waitcnt lgkmcnt(1)
	v_perm_b32 v16, v9, v8, s24
	s_waitcnt lgkmcnt(0)
	v_perm_b32 v17, v11, v10, s24
	s_mov_b32 s24, 0x7060302
	v_perm_b32 v4, v5, v4, s24
	v_perm_b32 v5, v7, v6, s24
	v_perm_b32 v6, v9, v8, s24
	v_ashrrev_i32_e32 v8, 31, v13
	v_perm_b32 v7, v11, v10, s24
	v_mul_lo_u32 v10, s23, v13
	v_mul_lo_u32 v11, s22, v8
	v_mad_u64_u32 v[8:9], s[24:25], s22, v13, 0
	v_add3_u32 v9, v9, v11, v10
	v_lshl_add_u64 v[8:9], v[8:9], 1, v[2:3]
	global_store_dwordx4 v[8:9], v[14:17], off sc1
	v_lshl_add_u64 v[8:9], s[22:23], 1, v[8:9]
	v_ashrrev_i32_e32 v12, 3, v12
	global_store_dwordx4 v[8:9], v[4:7], off sc1
	v_lshlrev_b32_e32 v13, 1, v12
	s_andn2_b64 vcc, exec, s[42:43]
	v_lshlrev_b32_e32 v4, 2, v12
	v_add3_u32 v1, 0, v4, v1
	ds_read2_b32 v[4:5], v1 offset1:129
	v_add_u32_e32 v6, 0x400, v1
	v_add_u32_e32 v8, 0x800, v1
	v_add_u32_e32 v1, 0xc00, v1
	ds_read2_b32 v[6:7], v6 offset0:2 offset1:131
	ds_read2_b32 v[8:9], v8 offset0:4 offset1:133
	ds_read2_b32 v[10:11], v1 offset0:6 offset1:135
	v_add_u32_e32 v12, s38, v13
	s_cbranch_vccnz .LBB0_645
	s_movk_i32 s24, 0x3ff
	v_cmp_lt_i32_e32 vcc, s24, v12
	s_and_b64 s[24:25], s[20:21], vcc
	v_mov_b32_e32 v1, v12
	s_and_saveexec_b64 s[20:21], s[24:25]
	v_add_u32_e32 v1, 0xfffffc00, v12
	v_lshlrev_b32_e32 v14, 1, v12
	v_lshrrev_b32_e32 v1, 3, v1
	v_and_b32_e32 v13, 0x7e, v13
	s_movk_i32 s24, 0x700
	v_and_b32_e32 v1, 0x1fffff80, v1
	v_and_or_b32 v13, v14, s24, v13
	s_movk_i32 s24, 0x400
	v_add3_u32 v1, v13, v1, s24
	s_or_b64 exec, exec, s[20:21]
	s_cbranch_execz .LBB0_646
	s_branch .LBB0_647

.LBB0_647:
	s_mov_b32 s20, 0x7060302
	s_waitcnt lgkmcnt(3)
	v_perm_b32 v12, v5, v4, s20
	s_waitcnt lgkmcnt(2)
	v_perm_b32 v13, v7, v6, s20
	s_waitcnt lgkmcnt(1)
	v_perm_b32 v14, v9, v8, s20
	s_waitcnt lgkmcnt(0)
	v_perm_b32 v15, v11, v10, s20
	s_mov_b32 s20, 0x5040100
	v_perm_b32 v4, v5, v4, s20
	v_perm_b32 v5, v7, v6, s20
	v_perm_b32 v6, v9, v8, s20
	v_ashrrev_i32_e32 v8, 31, v1
	v_perm_b32 v7, v11, v10, s20
	v_mul_lo_u32 v10, s23, v1
	v_mul_lo_u32 v11, s22, v8
	v_mad_u64_u32 v[8:9], s[20:21], s22, v1, 0
	v_add3_u32 v9, v9, v11, v10
	v_lshl_add_u64 v[2:3], v[8:9], 1, v[2:3]
	global_store_dwordx4 v[2:3], v[4:7], off sc1
	v_lshl_add_u64 v[2:3], s[22:23], 1, v[2:3]
	v_mov_b32_e32 v1, v0
	global_store_dwordx4 v[2:3], v[12:15], off sc1
	s_barrier
	s_nop 0
	v_cmp_eq_u32_e32 vcc, 0, v1
	s_and_saveexec_b64 s[20:21], vcc
	s_cbranch_execz .LBB0_651
	s_mov_b64 s[24:25], exec
	v_mbcnt_lo_u32_b32 v2, s24, 0
	v_mbcnt_hi_u32_b32 v2, s25, v2
	v_cmp_eq_u32_e32 vcc, 0, v2
	s_and_saveexec_b64 s[22:23], vcc
	s_cbranch_execz .LBB0_650
	s_bcnt1_i32_b64 s24, s[24:25]
	v_mov_b32_e32 v3, 0
	v_mov_b32_e32 v4, s24
	global_atomic_add v3, v3, v4, s[18:19] sc0

.LBB0_683:
	s_ashr_i32 s11, s10, 31
	s_lshl_b64 s[10:11], s[10:11], 1
	s_add_u32 s6, s6, s10
	s_addc_u32 s7, s7, s11
	v_lshlrev_b32_e32 v2, 1, v2
	v_mov_b32_e32 v3, 0
	v_lshl_add_u64 v[2:3], s[6:7], 0, v[2:3]
	s_mov_b32 s6, 0x5040100
	s_waitcnt lgkmcnt(3)
	v_perm_b32 v14, v5, v4, s6
	s_waitcnt lgkmcnt(2)
	v_perm_b32 v15, v7, v6, s6
	s_waitcnt lgkmcnt(1)
	v_perm_b32 v16, v9, v8, s6
	s_waitcnt lgkmcnt(0)
	v_perm_b32 v17, v11, v10, s6
	s_mov_b32 s6, 0x7060302
	v_perm_b32 v4, v5, v4, s6
	v_perm_b32 v5, v7, v6, s6
	v_perm_b32 v6, v9, v8, s6
	v_ashrrev_i32_e32 v8, 31, v13
	v_perm_b32 v7, v11, v10, s6
	v_mul_lo_u32 v10, s21, v13
	v_mul_lo_u32 v11, s20, v8
	v_mad_u64_u32 v[8:9], s[6:7], s20, v13, 0
	v_add3_u32 v9, v9, v11, v10
	v_lshl_add_u64 v[8:9], v[8:9], 1, v[2:3]
	global_store_dwordx4 v[8:9], v[14:17], off sc1
	v_lshl_add_u64 v[8:9], s[20:21], 1, v[8:9]
	v_ashrrev_i32_e32 v12, 3, v12
	global_store_dwordx4 v[8:9], v[4:7], off sc1
	v_lshlrev_b32_e32 v13, 1, v12
	s_andn2_b64 vcc, exec, s[12:13]
	v_lshlrev_b32_e32 v4, 2, v12
	v_add3_u32 v1, 0, v4, v1
	ds_read2_b32 v[4:5], v1 offset1:129
	v_add_u32_e32 v6, 0x400, v1
	v_add_u32_e32 v8, 0x800, v1
	v_add_u32_e32 v1, 0xc00, v1
	ds_read2_b32 v[6:7], v6 offset0:2 offset1:131
	ds_read2_b32 v[8:9], v8 offset0:4 offset1:133
	ds_read2_b32 v[10:11], v1 offset0:6 offset1:135
	v_add_u32_e32 v12, s8, v13
	s_cbranch_vccnz .LBB0_687
	s_movk_i32 s6, 0x3ff
	v_cmp_lt_i32_e32 vcc, s6, v12
	s_and_b64 s[8:9], s[18:19], vcc
	v_mov_b32_e32 v1, v12
	s_and_saveexec_b64 s[6:7], s[8:9]
	v_add_u32_e32 v1, 0xfffffc00, v12
	v_lshlrev_b32_e32 v14, 1, v12
	v_lshrrev_b32_e32 v1, 3, v1
	v_and_b32_e32 v13, 0x7e, v13
	s_movk_i32 s8, 0x700
	v_and_b32_e32 v1, 0x1fffff80, v1
	v_and_or_b32 v13, v14, s8, v13
	s_movk_i32 s8, 0x400
	v_add3_u32 v1, v13, v1, s8
	s_or_b64 exec, exec, s[6:7]
	s_mov_b64 s[6:7], 0
	s_branch .LBB0_688

.LBB0_690:
	s_mov_b32 s6, 0x7060302
	s_waitcnt lgkmcnt(3)
	v_perm_b32 v12, v5, v4, s6
	s_waitcnt lgkmcnt(2)
	v_perm_b32 v13, v7, v6, s6
	s_waitcnt lgkmcnt(1)
	v_perm_b32 v14, v9, v8, s6
	s_waitcnt lgkmcnt(0)
	v_perm_b32 v15, v11, v10, s6
	s_mov_b32 s6, 0x5040100
	v_perm_b32 v4, v5, v4, s6
	v_perm_b32 v5, v7, v6, s6
	v_perm_b32 v6, v9, v8, s6
	v_ashrrev_i32_e32 v8, 31, v1
	v_perm_b32 v7, v11, v10, s6
	v_mul_lo_u32 v10, s21, v1
	v_mul_lo_u32 v11, s20, v8
	v_mad_u64_u32 v[8:9], s[6:7], s20, v1, 0
	v_add3_u32 v9, v9, v11, v10
	v_lshl_add_u64 v[2:3], v[8:9], 1, v[2:3]
	global_store_dwordx4 v[2:3], v[4:7], off sc1
	v_lshl_add_u64 v[2:3], s[20:21], 1, v[2:3]
	global_store_dwordx4 v[2:3], v[12:15], off sc1
	s_barrier

.LBB0_736:
	s_waitcnt lgkmcnt(3)
	v_perm_b32 v16, v7, v6, s45
	s_waitcnt lgkmcnt(2)
	v_perm_b32 v17, v9, v8, s45
	s_waitcnt lgkmcnt(1)
	v_perm_b32 v18, v11, v10, s45
	v_perm_b32 v6, v7, v6, s44
	v_perm_b32 v7, v9, v8, s44
	v_perm_b32 v8, v11, v10, s44
	v_ashrrev_i32_e32 v10, 31, v2
	s_waitcnt lgkmcnt(0)
	v_perm_b32 v19, v13, v12, s45
	v_perm_b32 v9, v13, v12, s44
	v_mul_lo_u32 v12, s21, v2
	v_mul_lo_u32 v13, s20, v10
	v_mad_u64_u32 v[10:11], s[18:19], s20, v2, 0
	v_add3_u32 v11, v11, v13, v12
	s_add_i32 s28, s28, -1
	v_lshl_add_u64 v[4:5], v[10:11], 1, v[4:5]
	s_cmp_eq_u32 s28, 0
	global_store_dwordx4 v[4:5], v[6:9], off sc1
	v_lshl_add_u64 v[4:5], s[20:21], 1, v[4:5]
	s_cselect_b64 s[18:19], -1, 0
	global_store_dwordx4 v[4:5], v[16:19], off sc1
	s_barrier

.LBB0_768:
	s_ashr_i32 s43, s42, 31
	s_lshl_b64 s[24:25], s[42:43], 1
	s_add_u32 s22, s22, s24
	s_addc_u32 s23, s23, s25
	v_lshlrev_b32_e32 v2, 1, v2
	v_lshl_add_u64 v[4:5], s[22:23], 0, v[2:3]
	v_ashrrev_i32_e32 v2, 31, v17
	s_waitcnt lgkmcnt(3)
	v_perm_b32 v18, v7, v6, s44
	s_waitcnt lgkmcnt(2)
	v_perm_b32 v19, v9, v8, s44
	s_waitcnt lgkmcnt(1)
	v_perm_b32 v20, v11, v10, s44
	s_waitcnt lgkmcnt(0)
	v_perm_b32 v21, v13, v12, s44
	v_perm_b32 v6, v7, v6, s45
	v_perm_b32 v7, v9, v8, s45
	v_perm_b32 v8, v11, v10, s45
	v_perm_b32 v9, v13, v12, s45
	v_mul_lo_u32 v12, s21, v17
	v_mul_lo_u32 v2, s20, v2
	v_mad_u64_u32 v[10:11], s[22:23], s20, v17, 0
	v_add3_u32 v11, v11, v2, v12
	v_lshl_add_u64 v[10:11], v[10:11], 1, v[4:5]
	global_store_dwordx4 v[10:11], v[18:21], off sc1
	v_lshl_add_u64 v[10:11], s[20:21], 1, v[10:11]
	v_ashrrev_i32_e32 v2, 3, v15
	global_store_dwordx4 v[10:11], v[6:9], off sc1
	s_andn2_b64 vcc, exec, s[38:39]
	s_mov_b64 s[22:23], -1
	v_lshlrev_b32_e32 v6, 2, v2
	v_add3_u32 v12, 0, v6, v16
	ds_read2_b32 v[6:7], v12 offset1:129
	v_add_u32_e32 v8, 0x400, v12
	v_add_u32_e32 v10, 0x800, v12
	v_add_u32_e32 v12, 0xc00, v12
	ds_read2_b32 v[8:9], v8 offset0:2 offset1:131
	ds_read2_b32 v[10:11], v10 offset0:4 offset1:133
	ds_read2_b32 v[12:13], v12 offset0:6 offset1:135
	v_lshlrev_b32_e32 v16, 1, v2
	v_add_u32_e32 v15, s26, v16
	s_cbranch_vccnz .LBB0_772
	v_cmp_lt_i32_e32 vcc, s34, v15
	s_and_b64 s[22:23], s[18:19], vcc
	v_mov_b32_e32 v2, v15
	s_and_saveexec_b64 s[18:19], s[22:23]
	v_add_u32_e32 v2, 0xfffffc00, v15
	v_lshlrev_b32_e32 v17, 1, v15
	v_lshrrev_b32_e32 v2, 3, v2
	v_and_b32_e32 v16, 0x7e, v16
	v_and_b32_e32 v2, 0x1fffff80, v2
	v_and_or_b32 v16, v17, s35, v16
	v_add3_u32 v2, v16, v2, s30
	s_or_b64 exec, exec, s[18:19]
	s_mov_b64 s[22:23], 0

.LBB0_963:
	v_mov_b32_e32 v32, v0
	s_mov_b64 s[6:7], s[0:1]
	s_load_dwordx2 s[6:7], s[6:7], 0xe0
	v_lshlrev_b32_e32 v1, 3, v32
	v_and_b32_e32 v1, 0x1f8, v1
	v_lshlrev_b32_e32 v2, 1, v1
	v_ashrrev_i32_e32 v10, 6, v32
	s_waitcnt lgkmcnt(0)
	v_lshl_add_u64 v[4:5], s[6:7], 0, v[2:3]
	s_mov_b64 s[8:9], 0x4c00000
	v_ashrrev_i32_e32 v11, 31, v10
	v_lshl_add_u64 v[30:31], v[4:5], 0, s[8:9]
	v_lshl_add_u64 v[4:5], v[10:11], 0, s[4:5]
	v_mad_u64_u32 v[6:7], s[8:9], v4, s15, v[30:31]
	v_mad_i32_i24 v7, v5, s15, v7
	s_barrier
	global_load_dwordx4 v[6:9], v[6:7], off nt
	v_add_u32_e32 v33, 0, v2
	v_lshlrev_b32_e32 v1, 10, v10
	v_add_u32_e32 v1, v33, v1
	v_readfirstlane_b32 s10, v32
	s_cmpk_gt_u32 s10, 0x7f
	s_waitcnt vmcnt(0)
	ds_write_b128 v1, v[6:9]
	v_add_u32_e32 v6, 0x200, v32
	v_ashrrev_i32_e32 v12, 6, v6
	v_ashrrev_i32_e32 v13, 31, v12
	v_lshl_add_u64 v[6:7], v[12:13], 0, s[4:5]
	v_mad_u64_u32 v[8:9], s[8:9], v6, s15, v[30:31]
	v_mad_i32_i24 v9, v7, s15, v9
	global_load_dwordx4 v[8:11], v[8:9], off nt
	v_lshlrev_b32_e32 v12, 10, v12
	v_add_u32_e32 v20, v33, v12
	s_waitcnt vmcnt(0)
	ds_write_b128 v20, v[8:11]
	v_add_u32_e32 v8, 0x400, v32
	v_ashrrev_i32_e32 v14, 6, v8
	v_ashrrev_i32_e32 v15, 31, v14
	v_lshl_add_u64 v[8:9], v[14:15], 0, s[4:5]
	v_mad_u64_u32 v[10:11], s[8:9], v8, s15, v[30:31]
	v_mad_i32_i24 v11, v9, s15, v11
	global_load_dwordx4 v[10:13], v[10:11], off nt
	v_lshlrev_b32_e32 v14, 10, v14
	v_add_u32_e32 v21, v33, v14
	s_waitcnt vmcnt(0)
	ds_write_b128 v21, v[10:13]
	v_add_u32_e32 v10, 0x600, v32
	v_ashrrev_i32_e32 v16, 6, v10
	v_ashrrev_i32_e32 v17, 31, v16
	v_lshl_add_u64 v[10:11], v[16:17], 0, s[4:5]
	v_mad_u64_u32 v[12:13], s[8:9], v10, s15, v[30:31]
	v_mad_i32_i24 v13, v11, s15, v13
	global_load_dwordx4 v[12:15], v[12:13], off nt
	v_lshlrev_b32_e32 v16, 10, v16
	v_add_u32_e32 v22, v33, v16
	s_waitcnt vmcnt(0)
	ds_write_b128 v22, v[12:15]
	v_add_u32_e32 v12, 0x800, v32
	v_ashrrev_i32_e32 v18, 6, v12
	v_ashrrev_i32_e32 v19, 31, v18
	v_lshl_add_u64 v[12:13], v[18:19], 0, s[4:5]
	v_mad_u64_u32 v[14:15], s[8:9], v12, s15, v[30:31]
	v_mad_i32_i24 v15, v13, s15, v15
	global_load_dwordx4 v[14:17], v[14:15], off nt
	v_lshlrev_b32_e32 v18, 10, v18
	v_add_u32_e32 v23, v33, v18
	s_waitcnt vmcnt(0)
	ds_write_b128 v23, v[14:17]
	v_add_u32_e32 v14, 0xa00, v32
	v_ashrrev_i32_e32 v24, 6, v14
	v_ashrrev_i32_e32 v25, 31, v24
	v_lshl_add_u64 v[14:15], v[24:25], 0, s[4:5]
	v_mad_u64_u32 v[16:17], s[8:9], v14, s15, v[30:31]
	v_mad_i32_i24 v17, v15, s15, v17
	global_load_dwordx4 v[16:19], v[16:17], off nt
	v_lshlrev_b32_e32 v24, 10, v24
	v_add_u32_e32 v24, v33, v24
	s_waitcnt vmcnt(0)
	ds_write_b128 v24, v[16:19]
	v_add_u32_e32 v16, 0xc00, v32
	v_ashrrev_i32_e32 v18, 6, v16
	v_ashrrev_i32_e32 v19, 31, v18
	v_lshl_add_u64 v[16:17], v[18:19], 0, s[4:5]
	v_mad_u64_u32 v[26:27], s[8:9], v16, s15, v[30:31]
	v_mad_i32_i24 v27, v17, s15, v27
	global_load_dwordx4 v[26:29], v[26:27], off nt
	v_lshlrev_b32_e32 v18, 10, v18
	v_add_u32_e32 v25, v33, v18
	v_add_u32_e32 v18, 0xe00, v32
	s_waitcnt vmcnt(0)
	ds_write_b128 v25, v[26:29]
	v_ashrrev_i32_e32 v26, 6, v18
	v_ashrrev_i32_e32 v27, 31, v26
	v_lshl_add_u64 v[18:19], v[26:27], 0, s[4:5]
	v_mad_u64_u32 v[28:29], s[8:9], v18, s15, v[30:31]
	v_mad_i32_i24 v29, v19, s15, v29
	global_load_dwordx4 v[28:31], v[28:29], off nt
	v_lshlrev_b32_e32 v26, 10, v26
	v_add_u32_e32 v26, v33, v26
	v_lshl_add_u32 v27, v32, 1, 0
	s_mov_b64 s[8:9], -1
	s_waitcnt vmcnt(0)
	ds_write_b128 v26, v[28:31]
	s_waitcnt lgkmcnt(0)
	s_barrier
	s_cbranch_scc0 .LBB0_970
	ds_read_u16 v28, v27
	ds_read_u16 v29, v27 offset:1024
	ds_read_u16 v30, v27 offset:2048
	ds_read_u16 v31, v27 offset:3072
	ds_read_u16 v32, v27 offset:4096
	ds_read_u16 v34, v27 offset:5120
	ds_read_u16 v36, v27 offset:6144
	ds_read_u16 v37, v27 offset:7168
	s_waitcnt lgkmcnt(7)
	v_lshlrev_b32_e32 v61, 16, v28
	v_add_f32_e32 v42, 0, v61
	s_waitcnt lgkmcnt(6)
	v_lshlrev_b32_e32 v60, 16, v29
	v_add_f32_e32 v38, v42, v60
	s_waitcnt lgkmcnt(5)
	v_lshlrev_b32_e32 v55, 16, v30
	v_add_f32_e32 v35, v38, v55
	s_waitcnt lgkmcnt(4)
	v_lshlrev_b32_e32 v50, 16, v31
	v_add_f32_e32 v33, v35, v50
	s_waitcnt lgkmcnt(3)
	v_lshlrev_b32_e32 v46, 16, v32
	v_add_f32_e32 v31, v33, v46
	s_waitcnt lgkmcnt(2)
	v_lshlrev_b32_e32 v43, 16, v34
	v_add_f32_e32 v30, v31, v43
	s_waitcnt lgkmcnt(1)
	v_lshlrev_b32_e32 v39, 16, v36
	v_add_f32_e32 v29, v30, v39
	s_waitcnt lgkmcnt(0)
	v_lshlrev_b32_e32 v36, 16, v37
	v_add_f32_e32 v28, v29, v36
	ds_read_u16 v32, v27 offset:8192
	ds_read_u16 v34, v27 offset:9216
	ds_read_u16 v37, v27 offset:10240
	ds_read_u16 v40, v27 offset:11264
	ds_read_u16 v41, v27 offset:12288
	ds_read_u16 v45, v27 offset:13312
	ds_read_u16 v48, v27 offset:14336
	ds_read_u16 v49, v27 offset:15360
	s_waitcnt lgkmcnt(7)
	v_lshlrev_b32_e32 v81, 16, v32
	v_add_f32_e32 v56, v28, v81
	s_waitcnt lgkmcnt(6)
	v_lshlrev_b32_e32 v76, 16, v34
	v_add_f32_e32 v51, v56, v76
	s_waitcnt lgkmcnt(5)
	v_lshlrev_b32_e32 v71, 16, v37
	v_add_f32_e32 v47, v51, v71
	s_waitcnt lgkmcnt(4)
	v_lshlrev_b32_e32 v66, 16, v40
	v_add_f32_e32 v44, v47, v66
	s_waitcnt lgkmcnt(3)
	v_lshlrev_b32_e32 v62, 16, v41
	v_add_f32_e32 v40, v44, v62
	s_waitcnt lgkmcnt(2)
	v_lshlrev_b32_e32 v57, 16, v45
	v_add_f32_e32 v37, v40, v57
	s_waitcnt lgkmcnt(1)
	v_lshlrev_b32_e32 v52, 16, v48
	v_add_f32_e32 v34, v37, v52
	s_waitcnt lgkmcnt(0)
	v_lshlrev_b32_e32 v48, 16, v49
	v_add_f32_e32 v32, v34, v48
	ds_read_u16 v41, v27 offset:16384
	ds_read_u16 v45, v27 offset:17408
	ds_read_u16 v49, v27 offset:18432
	ds_read_u16 v53, v27 offset:19456
	ds_read_u16 v54, v27 offset:20480
	ds_read_u16 v59, v27 offset:21504
	ds_read_u16 v64, v27 offset:22528
	ds_read_u16 v65, v27 offset:23552
	s_waitcnt lgkmcnt(7)
	v_lshlrev_b32_e32 v97, 16, v41
	v_add_f32_e32 v72, v32, v97
	s_waitcnt lgkmcnt(6)
	v_lshlrev_b32_e32 v92, 16, v45
	v_add_f32_e32 v67, v72, v92
	s_waitcnt lgkmcnt(5)
	v_lshlrev_b32_e32 v87, 16, v49
	v_add_f32_e32 v63, v67, v87
	s_waitcnt lgkmcnt(4)
	v_lshlrev_b32_e32 v82, 16, v53
	v_add_f32_e32 v58, v63, v82
	s_waitcnt lgkmcnt(3)
	v_lshlrev_b32_e32 v77, 16, v54
	v_add_f32_e32 v53, v58, v77
	s_waitcnt lgkmcnt(2)
	v_lshlrev_b32_e32 v73, 16, v59
	v_add_f32_e32 v49, v53, v73
	s_waitcnt lgkmcnt(1)
	v_lshlrev_b32_e32 v68, 16, v64
	v_add_f32_e32 v45, v49, v68
	s_waitcnt lgkmcnt(0)
	v_lshlrev_b32_e32 v64, 16, v65
	v_add_f32_e32 v41, v45, v64
	ds_read_u16 v54, v27 offset:24576
	ds_read_u16 v59, v27 offset:25600
	ds_read_u16 v65, v27 offset:26624
	ds_read_u16 v69, v27 offset:27648
	ds_read_u16 v70, v27 offset:28672
	ds_read_u16 v75, v27 offset:29696
	ds_read_u16 v79, v27 offset:30720
	ds_read_u16 v80, v27 offset:31744
	s_waitcnt lgkmcnt(7)
	v_lshlrev_b32_e32 v113, 16, v54
	v_add_f32_e32 v88, v41, v113
	s_waitcnt lgkmcnt(6)
	v_lshlrev_b32_e32 v108, 16, v59
	v_add_f32_e32 v83, v88, v108
	s_waitcnt lgkmcnt(5)
	v_lshlrev_b32_e32 v103, 16, v65
	v_add_f32_e32 v78, v83, v103
	s_waitcnt lgkmcnt(4)
	v_lshlrev_b32_e32 v98, 16, v69
	v_add_f32_e32 v74, v78, v98
	s_waitcnt lgkmcnt(3)
	v_lshlrev_b32_e32 v93, 16, v70
	v_add_f32_e32 v69, v74, v93
	s_waitcnt lgkmcnt(2)
	v_lshlrev_b32_e32 v89, 16, v75
	v_add_f32_e32 v65, v69, v89
	s_waitcnt lgkmcnt(1)
	v_lshlrev_b32_e32 v84, 16, v79
	v_add_f32_e32 v59, v65, v84
	s_waitcnt lgkmcnt(0)
	v_lshlrev_b32_e32 v79, 16, v80
	v_add_f32_e32 v54, v59, v79
	ds_read_u16 v70, v27 offset:32768
	ds_read_u16 v75, v27 offset:33792
	ds_read_u16 v80, v27 offset:34816
	ds_read_u16 v85, v27 offset:35840
	ds_read_u16 v86, v27 offset:36864
	ds_read_u16 v91, v27 offset:37888
	ds_read_u16 v95, v27 offset:38912
	ds_read_u16 v96, v27 offset:39936
	s_waitcnt lgkmcnt(7)
	v_lshlrev_b32_e32 v126, 16, v70
	v_add_f32_e32 v104, v54, v126
	s_waitcnt lgkmcnt(6)
	v_lshlrev_b32_e32 v122, 16, v75
	v_add_f32_e32 v99, v104, v122
	s_waitcnt lgkmcnt(5)
	v_lshlrev_b32_e32 v118, 16, v80
	v_add_f32_e32 v94, v99, v118
	s_waitcnt lgkmcnt(4)
	v_lshlrev_b32_e32 v114, 16, v85
	v_add_f32_e32 v90, v94, v114
	s_waitcnt lgkmcnt(3)
	v_lshlrev_b32_e32 v109, 16, v86
	v_add_f32_e32 v85, v90, v109
	s_waitcnt lgkmcnt(2)
	v_lshlrev_b32_e32 v105, 16, v91
	v_add_f32_e32 v80, v85, v105
	s_waitcnt lgkmcnt(1)
	v_lshlrev_b32_e32 v100, 16, v95
	v_add_f32_e32 v75, v80, v100
	s_waitcnt lgkmcnt(0)
	v_lshlrev_b32_e32 v95, 16, v96
	v_add_f32_e32 v70, v75, v95
	ds_read_u16 v86, v27 offset:40960
	ds_read_u16 v91, v27 offset:41984
	ds_read_u16 v96, v27 offset:43008
	ds_read_u16 v101, v27 offset:44032
	ds_read_u16 v102, v27 offset:45056
	ds_read_u16 v107, v27 offset:46080
	ds_read_u16 v111, v27 offset:47104
	ds_read_u16 v112, v27 offset:48128
	s_waitcnt lgkmcnt(7)
	v_lshlrev_b32_e32 v139, 16, v86
	v_add_f32_e32 v119, v70, v139
	s_waitcnt lgkmcnt(6)
	v_lshlrev_b32_e32 v135, 16, v91
	v_add_f32_e32 v115, v119, v135
	s_waitcnt lgkmcnt(5)
	v_lshlrev_b32_e32 v131, 16, v96
	v_add_f32_e32 v110, v115, v131
	s_waitcnt lgkmcnt(4)
	v_lshlrev_b32_e32 v127, 16, v101
	v_add_f32_e32 v106, v110, v127
	s_waitcnt lgkmcnt(3)
	v_lshlrev_b32_e32 v123, 16, v102
	v_add_f32_e32 v101, v106, v123
	s_waitcnt lgkmcnt(2)
	v_lshlrev_b32_e32 v120, 16, v107
	v_add_f32_e32 v96, v101, v120
	s_waitcnt lgkmcnt(1)
	v_lshlrev_b32_e32 v116, 16, v111
	v_add_f32_e32 v91, v96, v116
	s_waitcnt lgkmcnt(0)
	v_lshlrev_b32_e32 v111, 16, v112
	v_add_f32_e32 v86, v91, v111
	ds_read_u16 v102, v27 offset:49152
	ds_read_u16 v107, v27 offset:50176
	ds_read_u16 v112, v27 offset:51200
	ds_read_u16 v117, v27 offset:52224
	ds_read_u16 v125, v27 offset:53248
	ds_read_u16 v129, v27 offset:54272
	ds_read_u16 v130, v27 offset:55296
	ds_read_u16 v134, v27 offset:56320
	s_waitcnt lgkmcnt(7)
	v_lshlrev_b32_e32 v149, 16, v102
	v_add_f32_e32 v132, v86, v149
	s_waitcnt lgkmcnt(6)
	v_lshlrev_b32_e32 v147, 16, v107
	v_add_f32_e32 v128, v132, v147
	s_waitcnt lgkmcnt(5)
	v_lshlrev_b32_e32 v144, 16, v112
	v_add_f32_e32 v124, v128, v144
	s_waitcnt lgkmcnt(4)
	v_lshlrev_b32_e32 v140, 16, v117
	v_add_f32_e32 v121, v124, v140
	s_waitcnt lgkmcnt(3)
	v_lshlrev_b32_e32 v136, 16, v125
	v_add_f32_e32 v117, v121, v136
	s_waitcnt lgkmcnt(2)
	v_lshlrev_b32_e32 v133, 16, v129
	v_add_f32_e32 v112, v117, v133
	s_waitcnt lgkmcnt(1)
	v_lshlrev_b32_e32 v129, 16, v130
	v_add_f32_e32 v107, v112, v129
	s_waitcnt lgkmcnt(0)
	v_lshlrev_b32_e32 v125, 16, v134
	v_add_f32_e32 v102, v107, v125
	ds_read_u16 v130, v27 offset:57344
	ds_read_u16 v134, v27 offset:58368
	ds_read_u16 v137, v27 offset:59392
	ds_read_u16 v138, v27 offset:60416
	ds_read_u16 v142, v27 offset:61440
	ds_read_u16 v143, v27 offset:62464
	ds_read_u16 v151, v27 offset:63488
	ds_read_u16 v156, v27 offset:64512
	s_waitcnt lgkmcnt(7)
	v_lshlrev_b32_e32 v155, 16, v130
	v_add_f32_e32 v145, v102, v155
	s_waitcnt lgkmcnt(6)
	v_lshlrev_b32_e32 v154, 16, v134
	v_add_f32_e32 v141, v145, v154
	s_waitcnt lgkmcnt(5)
	v_lshlrev_b32_e32 v152, 16, v137
	v_add_f32_e32 v137, v141, v152
	s_waitcnt lgkmcnt(4)
	v_lshlrev_b32_e32 v150, 16, v138
	v_add_f32_e32 v134, v137, v150
	s_waitcnt lgkmcnt(3)
	v_lshlrev_b32_e32 v148, 16, v142
	v_add_f32_e32 v130, v134, v148
	s_waitcnt lgkmcnt(2)
	v_lshlrev_b32_e32 v146, 16, v143
	v_add_f32_e32 v153, v130, v146
	s_waitcnt lgkmcnt(1)
	v_lshlrev_b32_e32 v142, 16, v151
	s_ashr_i32 s35, s10, 7
	v_add_f32_e32 v151, v153, v142
	s_waitcnt lgkmcnt(0)
	v_lshlrev_b32_e32 v138, 16, v156
	v_add_f32_e32 v143, v151, v138
	s_mov_b64 s[12:13], -1
	s_mov_b64 s[8:9], 0
	s_cmp_lt_i32 s35, 2
	s_mov_b64 s[10:11], 0
	s_cbranch_scc0 .LBB0_972
	s_and_b64 vcc, exec, s[12:13]
	s_cbranch_vccnz .LBB0_975

.LBB0_1012:
	s_ashr_i32 s41, s40, 31
	s_lshl_b64 s[24:25], s[40:41], 1
	s_add_u32 s22, s22, s24
	s_addc_u32 s23, s23, s25
	v_lshlrev_b32_e32 v2, 1, v2
	v_mov_b32_e32 v3, 0
	v_lshl_add_u64 v[2:3], s[22:23], 0, v[2:3]
	s_mov_b32 s22, 0x5040100
	s_waitcnt lgkmcnt(3)
	v_perm_b32 v14, v5, v4, s22
	s_waitcnt lgkmcnt(2)
	v_perm_b32 v15, v7, v6, s22
	s_waitcnt lgkmcnt(1)
	v_perm_b32 v16, v9, v8, s22
	s_waitcnt lgkmcnt(0)
	v_perm_b32 v17, v11, v10, s22
	s_mov_b32 s22, 0x7060302
	v_perm_b32 v4, v5, v4, s22
	v_perm_b32 v5, v7, v6, s22
	v_perm_b32 v6, v9, v8, s22
	v_ashrrev_i32_e32 v8, 31, v13
	v_perm_b32 v7, v11, v10, s22
	v_mul_lo_u32 v10, s21, v13
	v_mul_lo_u32 v11, s20, v8
	v_mad_u64_u32 v[8:9], s[22:23], s20, v13, 0
	v_add3_u32 v9, v9, v11, v10
	v_lshl_add_u64 v[8:9], v[8:9], 1, v[2:3]
	global_store_dwordx4 v[8:9], v[14:17], off sc1
	v_lshl_add_u64 v[8:9], s[20:21], 1, v[8:9]
	v_ashrrev_i32_e32 v12, 3, v12
	global_store_dwordx4 v[8:9], v[4:7], off sc1
	v_lshlrev_b32_e32 v13, 1, v12
	s_andn2_b64 vcc, exec, s[38:39]
	v_lshlrev_b32_e32 v4, 2, v12
	v_add3_u32 v1, 0, v4, v1
	ds_read2_b32 v[4:5], v1 offset1:129
	v_add_u32_e32 v6, 0x400, v1
	v_add_u32_e32 v8, 0x800, v1
	v_add_u32_e32 v1, 0xc00, v1
	ds_read2_b32 v[6:7], v6 offset0:2 offset1:131
	ds_read2_b32 v[8:9], v8 offset0:4 offset1:133
	ds_read2_b32 v[10:11], v1 offset0:6 offset1:135
	v_add_u32_e32 v12, s26, v13
	s_cbranch_vccnz .LBB0_1016
	s_movk_i32 s22, 0x3ff
	v_cmp_lt_i32_e32 vcc, s22, v12
	s_and_b64 s[22:23], s[18:19], vcc
	v_mov_b32_e32 v1, v12
	s_and_saveexec_b64 s[18:19], s[22:23]
	v_add_u32_e32 v1, 0xfffffc00, v12
	v_lshlrev_b32_e32 v14, 1, v12
	v_lshrrev_b32_e32 v1, 3, v1
	v_and_b32_e32 v13, 0x7e, v13
	s_movk_i32 s22, 0x700
	v_and_b32_e32 v1, 0x1fffff80, v1
	v_and_or_b32 v13, v14, s22, v13
	s_movk_i32 s22, 0x400
	v_add3_u32 v1, v13, v1, s22
	s_or_b64 exec, exec, s[18:19]
	s_cbranch_execz .LBB0_1017
	s_branch .LBB0_1018

.LBB0_1018:
	s_mov_b32 s18, 0x7060302
	s_waitcnt lgkmcnt(3)
	v_perm_b32 v12, v5, v4, s18
	s_waitcnt lgkmcnt(2)
	v_perm_b32 v13, v7, v6, s18
	s_waitcnt lgkmcnt(1)
	v_perm_b32 v14, v9, v8, s18
	s_waitcnt lgkmcnt(0)
	v_perm_b32 v15, v11, v10, s18
	s_mov_b32 s18, 0x5040100
	v_perm_b32 v4, v5, v4, s18
	v_perm_b32 v5, v7, v6, s18
	v_perm_b32 v6, v9, v8, s18
	v_ashrrev_i32_e32 v8, 31, v1
	v_perm_b32 v7, v11, v10, s18
	v_mul_lo_u32 v10, s21, v1
	v_mul_lo_u32 v11, s20, v8
	v_mad_u64_u32 v[8:9], s[18:19], s20, v1, 0
	v_add3_u32 v9, v9, v11, v10
	v_lshl_add_u64 v[2:3], v[8:9], 1, v[2:3]
	global_store_dwordx4 v[2:3], v[4:7], off sc1
	v_lshl_add_u64 v[2:3], s[20:21], 1, v[2:3]
	v_mov_b32_e32 v1, v0
	global_store_dwordx4 v[2:3], v[12:15], off sc1
	s_barrier
	s_nop 0
	v_cmp_eq_u32_e32 vcc, 0, v1
	s_and_saveexec_b64 s[18:19], vcc
	s_cbranch_execz .LBB0_1022
	s_mov_b64 s[22:23], exec
	v_mbcnt_lo_u32_b32 v2, s22, 0
	v_mbcnt_hi_u32_b32 v2, s23, v2
	v_cmp_eq_u32_e32 vcc, 0, v2
	s_and_saveexec_b64 s[20:21], vcc
	s_cbranch_execz .LBB0_1021
	s_bcnt1_i32_b64 s22, s[22:23]
	v_mov_b32_e32 v3, 0
	v_mov_b32_e32 v4, s22
	global_atomic_add v3, v3, v4, s[16:17] sc0

.LBB0_1053:
	s_ashr_i32 s9, s8, 31
	s_lshl_b64 s[8:9], s[8:9], 1
	s_add_u32 s4, s4, s8
	s_addc_u32 s5, s5, s9
	v_lshlrev_b32_e32 v2, 1, v2
	v_mov_b32_e32 v3, 0
	v_lshl_add_u64 v[2:3], s[4:5], 0, v[2:3]
	s_mov_b32 s4, 0x5040100
	s_waitcnt lgkmcnt(3)
	v_perm_b32 v14, v5, v4, s4
	s_waitcnt lgkmcnt(2)
	v_perm_b32 v15, v7, v6, s4
	s_waitcnt lgkmcnt(1)
	v_perm_b32 v16, v9, v8, s4
	s_waitcnt lgkmcnt(0)
	v_perm_b32 v17, v11, v10, s4
	s_mov_b32 s4, 0x7060302
	v_perm_b32 v4, v5, v4, s4
	v_perm_b32 v5, v7, v6, s4
	v_perm_b32 v6, v9, v8, s4
	v_ashrrev_i32_e32 v8, 31, v13
	v_perm_b32 v7, v11, v10, s4
	v_mul_lo_u32 v10, s19, v13
	v_mul_lo_u32 v11, s18, v8
	v_mad_u64_u32 v[8:9], s[4:5], s18, v13, 0
	v_add3_u32 v9, v9, v11, v10
	v_lshl_add_u64 v[8:9], v[8:9], 1, v[2:3]
	global_store_dwordx4 v[8:9], v[14:17], off sc1
	v_lshl_add_u64 v[8:9], s[18:19], 1, v[8:9]
	v_ashrrev_i32_e32 v12, 3, v12
	global_store_dwordx4 v[8:9], v[4:7], off sc1
	v_lshlrev_b32_e32 v13, 1, v12
	s_andn2_b64 vcc, exec, s[10:11]
	v_lshlrev_b32_e32 v4, 2, v12
	v_add3_u32 v1, 0, v4, v1
	ds_read2_b32 v[4:5], v1 offset1:129
	v_add_u32_e32 v6, 0x400, v1
	v_add_u32_e32 v8, 0x800, v1
	v_add_u32_e32 v1, 0xc00, v1
	ds_read2_b32 v[6:7], v6 offset0:2 offset1:131
	ds_read2_b32 v[8:9], v8 offset0:4 offset1:133
	ds_read2_b32 v[10:11], v1 offset0:6 offset1:135
	v_add_u32_e32 v12, s6, v13
	s_cbranch_vccnz .LBB0_1057
	s_movk_i32 s4, 0x3ff
	v_cmp_lt_i32_e32 vcc, s4, v12
	s_and_b64 s[6:7], s[16:17], vcc
	v_mov_b32_e32 v1, v12
	s_and_saveexec_b64 s[4:5], s[6:7]
	v_add_u32_e32 v1, 0xfffffc00, v12
	v_lshlrev_b32_e32 v14, 1, v12
	v_lshrrev_b32_e32 v1, 3, v1
	v_and_b32_e32 v13, 0x7e, v13
	s_movk_i32 s6, 0x700
	v_and_b32_e32 v1, 0x1fffff80, v1
	v_and_or_b32 v13, v14, s6, v13
	s_movk_i32 s6, 0x400
	v_add3_u32 v1, v13, v1, s6
	s_or_b64 exec, exec, s[4:5]
	s_cbranch_execz .LBB0_1058
	s_branch .LBB0_1059

.LBB0_1059:
	s_mov_b32 s4, 0x7060302
	s_waitcnt lgkmcnt(3)
	v_perm_b32 v12, v5, v4, s4
	s_waitcnt lgkmcnt(2)
	v_perm_b32 v13, v7, v6, s4
	s_waitcnt lgkmcnt(1)
	v_perm_b32 v14, v9, v8, s4
	s_waitcnt lgkmcnt(0)
	v_perm_b32 v15, v11, v10, s4
	s_mov_b32 s4, 0x5040100
	v_perm_b32 v4, v5, v4, s4
	v_perm_b32 v5, v7, v6, s4
	v_perm_b32 v6, v9, v8, s4
	v_ashrrev_i32_e32 v8, 31, v1
	v_perm_b32 v7, v11, v10, s4
	v_mul_lo_u32 v10, s19, v1
	v_mul_lo_u32 v11, s18, v8
	v_mad_u64_u32 v[8:9], s[4:5], s18, v1, 0
	v_add3_u32 v9, v9, v11, v10
	v_lshl_add_u64 v[2:3], v[8:9], 1, v[2:3]
	global_store_dwordx4 v[2:3], v[4:7], off sc1
	v_lshl_add_u64 v[2:3], s[18:19], 1, v[2:3]
	global_store_dwordx4 v[2:3], v[12:15], off sc1
	s_barrier
